# GEMM k-loops: peeled last iteration (no clamped dummy loads / dead LDS writes), top-tested main loop + tail
# speedup vs baseline: 1.2180x; 1.0209x over previous
; #define G_STORE(ST, S, unused) do { char* d_ = smem + (ST) * STAGE; \
;     *(uint4*)(d_ + alo[0]) = S##a0; *(uint4*)(d_ + alo[1]) = S##a1; *(uint4*)(d_ + alo[2]) = S##a2; *(uint4*)(d_ + alo[3]) = S##a3; \
;     *(uint4*)(d_ + blo[0]) = S##b0; *(uint4*)(d_ + blo[1]) = S##b1; \
;     if (NBCH == 4) { *(uint4*)(d_ + blo[NBCH - 2]) = S##b2; *(uint4*)(d_ + blo[NBCH - 1]) = S##b3; } } while (0)
; template <int NJ, class RowA>
; DI void gemm_main(f32x16 (&acc)[2][NJ], const bf16_t* __restrict__ A, RowA rowA, size_t kstrideA, int m0, int Mmax,
;                   const bf16_t* __restrict__ Bt, size_t ldb, int n0, int nk, char* smem) {
;     ...
;   __syncthreads();
;   G_LOAD(x0, 0, 0);
;   G_LOAD(x1, 0, 1);
;   G_STORE(0, x0, 0);
;   __syncthreads();
; #pragma unroll 1
;   for (int kt = 0; kt < nk; kt += 2) {
;     G_LOAD(x0, 0, (kt + 2 < nk ? kt + 2 : nk - 1));
;     G_COMPUTE(0);
;     G_STORE(1, x1, 0);
;     __syncthreads();
;     G_LOAD(x1, 0, (kt + 3 < nk ? kt + 3 : nk - 1));
;     G_COMPUTE(1);
;     G_STORE(0, x0, 0);
;     __syncthreads();
;   }
.LBB0_12:
	s_cmp_lt_i32 s3, 12
	s_cbranch_scc0 .Lpeel_tail_12
	ds_read_b128 v[166:169], v0
	ds_read_b128 v[170:173], v139 offset:18432
	ds_read_b128 v[174:177], v139 offset:23040
	ds_read_b128 v[178:181], v0 offset:4608
	s_add_i32 s4, s3, 4
	s_min_u32 s4, s4, 15
	s_lshl_b32 s14, s4, 7
	v_lshl_add_u64 v[98:99], v[122:123], 0, s[14:15]
	v_lshl_add_u64 v[102:103], v[124:125], 0, s[14:15]
	v_lshl_add_u64 v[106:107], v[126:127], 0, s[14:15]
	v_lshl_add_u64 v[110:111], v[128:129], 0, s[14:15]
	v_lshl_add_u64 v[114:115], v[130:131], 0, s[14:15]
	v_lshl_add_u64 v[118:119], v[132:133], 0, s[14:15]
	s_add_i32 s3, s3, 2
	v_lshl_add_u64 v[158:159], v[134:135], 0, s[14:15]
	v_lshl_add_u64 v[160:161], v[136:137], 0, s[14:15]
	s_setprio 1
	ds_read_b128 v[182:185], v0 offset:32
	ds_read_b128 v[186:189], v139 offset:18464
	ds_read_b128 v[190:193], v139 offset:23072
	ds_read_b128 v[194:197], v0 offset:4640
	s_waitcnt lgkmcnt(4)
	v_mfma_f32_32x32x16_bf16 v[50:65], v[166:169], v[170:173], v[50:65]
	global_load_dwordx4 v[98:101], v[98:99], off
	v_mfma_f32_32x32x16_bf16 v[34:49], v[166:169], v[174:177], v[34:49]
	global_load_dwordx4 v[102:105], v[102:103], off
	v_mfma_f32_32x32x16_bf16 v[18:33], v[178:181], v[170:173], v[18:33]
	global_load_dwordx4 v[106:109], v[106:107], off
	v_mfma_f32_32x32x16_bf16 v[2:17], v[178:181], v[174:177], v[2:17]
	global_load_dwordx4 v[110:113], v[110:111], off
	ds_read_b128 v[166:169], v0 offset:64
	ds_read_b128 v[170:173], v139 offset:18496
	ds_read_b128 v[174:177], v139 offset:23104
	ds_read_b128 v[178:181], v0 offset:4672
	s_waitcnt lgkmcnt(4)
	v_mfma_f32_32x32x16_bf16 v[50:65], v[182:185], v[186:189], v[50:65]
	global_load_dwordx4 v[114:117], v[114:115], off
	v_mfma_f32_32x32x16_bf16 v[34:49], v[182:185], v[190:193], v[34:49]
	global_load_dwordx4 v[118:121], v[118:119], off
	v_mfma_f32_32x32x16_bf16 v[18:33], v[194:197], v[186:189], v[18:33]
	global_load_dwordx4 v[146:149], v[160:161], off
	v_mfma_f32_32x32x16_bf16 v[2:17], v[194:197], v[190:193], v[2:17]
	global_load_dwordx4 v[150:153], v[158:159], off
	ds_read_b128 v[182:185], v0 offset:96
	ds_read_b128 v[186:189], v139 offset:18528
	ds_read_b128 v[190:193], v139 offset:23136
	ds_read_b128 v[194:197], v0 offset:4704
	s_waitcnt lgkmcnt(4)
	v_mfma_f32_32x32x16_bf16 v[50:65], v[166:169], v[170:173], v[50:65]
	s_waitcnt vmcnt(8)
	ds_write_b128 v138, v[78:81] offset:36864
	v_mfma_f32_32x32x16_bf16 v[34:49], v[166:169], v[174:177], v[34:49]
	ds_write_b128 v140, v[86:89] offset:36864
	v_mfma_f32_32x32x16_bf16 v[18:33], v[178:181], v[170:173], v[18:33]
	ds_write_b128 v142, v[90:93] offset:36864
	v_mfma_f32_32x32x16_bf16 v[2:17], v[178:181], v[174:177], v[2:17]
	ds_write_b128 v144, v[94:97] offset:36864
	s_waitcnt lgkmcnt(4)
	v_mfma_f32_32x32x16_bf16 v[50:65], v[182:185], v[186:189], v[50:65]
	ds_write_b128 v138, v[74:77] offset:55296
	v_mfma_f32_32x32x16_bf16 v[34:49], v[182:185], v[190:193], v[34:49]
	ds_write_b128 v140, v[82:85] offset:55296
	v_mfma_f32_32x32x16_bf16 v[18:33], v[194:197], v[186:189], v[18:33]
	ds_write_b128 v142, v[66:69] offset:55296
	v_mfma_f32_32x32x16_bf16 v[2:17], v[194:197], v[190:193], v[2:17]
	ds_write_b128 v144, v[70:73] offset:55296
	s_setprio 0
	s_min_u32 s4, s3, 12
	s_lshl_b32 s14, s4, 7
	v_lshl_add_u64 v[66:67], v[122:123], 0, s[14:15]
	v_lshl_add_u64 v[68:69], v[124:125], 0, s[14:15]
	v_lshl_add_u64 v[70:71], v[126:127], 0, s[14:15]
	v_lshl_add_u64 v[72:73], v[128:129], 0, s[14:15]
	v_lshl_add_u64 v[74:75], v[130:131], 0, s[14:15]
	v_lshl_add_u64 v[82:83], v[132:133], 0, s[14:15]
	s_waitcnt lgkmcnt(0)
	s_barrier
	ds_read_b128 v[166:169], v0 offset:36864
	ds_read_b128 v[170:173], v139 offset:55296
	ds_read_b128 v[174:177], v139 offset:59904
	ds_read_b128 v[178:181], v0 offset:41472
	v_lshl_add_u64 v[154:155], v[134:135], 0, s[14:15]
	v_lshl_add_u64 v[156:157], v[136:137], 0, s[14:15]
	s_setprio 1
	ds_read_b128 v[182:185], v0 offset:36896
	ds_read_b128 v[186:189], v139 offset:55328
	ds_read_b128 v[190:193], v139 offset:59936
	ds_read_b128 v[194:197], v0 offset:41504
	s_waitcnt lgkmcnt(4)
	v_mfma_f32_32x32x16_bf16 v[50:65], v[166:169], v[170:173], v[50:65]
	global_load_dwordx4 v[78:81], v[66:67], off offset:384
	v_mfma_f32_32x32x16_bf16 v[34:49], v[166:169], v[174:177], v[34:49]
	global_load_dwordx4 v[86:89], v[68:69], off offset:384
	v_mfma_f32_32x32x16_bf16 v[18:33], v[178:181], v[170:173], v[18:33]
	global_load_dwordx4 v[90:93], v[70:71], off offset:384
	v_mfma_f32_32x32x16_bf16 v[2:17], v[178:181], v[174:177], v[2:17]
	global_load_dwordx4 v[94:97], v[72:73], off offset:384
	ds_read_b128 v[166:169], v0 offset:36928
	ds_read_b128 v[170:173], v139 offset:55360
	ds_read_b128 v[174:177], v139 offset:59968
	ds_read_b128 v[178:181], v0 offset:41536
	s_waitcnt lgkmcnt(4)
	v_mfma_f32_32x32x16_bf16 v[50:65], v[182:185], v[186:189], v[50:65]
	global_load_dwordx4 v[74:77], v[74:75], off offset:384
	v_mfma_f32_32x32x16_bf16 v[34:49], v[182:185], v[190:193], v[34:49]
	global_load_dwordx4 v[82:85], v[82:83], off offset:384
	v_mfma_f32_32x32x16_bf16 v[18:33], v[194:197], v[186:189], v[18:33]
	global_load_dwordx4 v[66:69], v[154:155], off offset:384
	v_mfma_f32_32x32x16_bf16 v[2:17], v[194:197], v[190:193], v[2:17]
	global_load_dwordx4 v[70:73], v[156:157], off offset:384
	ds_read_b128 v[182:185], v0 offset:36960
	ds_read_b128 v[186:189], v139 offset:55392
	ds_read_b128 v[190:193], v139 offset:60000
	ds_read_b128 v[194:197], v0 offset:41568
	s_waitcnt lgkmcnt(4)
	v_mfma_f32_32x32x16_bf16 v[50:65], v[166:169], v[170:173], v[50:65]
	s_waitcnt vmcnt(8)
	ds_write_b128 v138, v[98:101]
	v_mfma_f32_32x32x16_bf16 v[34:49], v[166:169], v[174:177], v[34:49]
	ds_write_b128 v140, v[102:105]
	v_mfma_f32_32x32x16_bf16 v[18:33], v[178:181], v[170:173], v[18:33]
	ds_write_b128 v142, v[106:109]
	v_mfma_f32_32x32x16_bf16 v[2:17], v[178:181], v[174:177], v[2:17]
	ds_write_b128 v144, v[110:113]
	s_waitcnt lgkmcnt(4)
	v_mfma_f32_32x32x16_bf16 v[50:65], v[182:185], v[186:189], v[50:65]
	ds_write_b128 v138, v[114:117] offset:18432
	v_mfma_f32_32x32x16_bf16 v[34:49], v[182:185], v[190:193], v[34:49]
	ds_write_b128 v140, v[118:121] offset:18432
	v_mfma_f32_32x32x16_bf16 v[18:33], v[194:197], v[186:189], v[18:33]
	ds_write_b128 v142, v[150:153] offset:18432
	v_mfma_f32_32x32x16_bf16 v[2:17], v[194:197], v[190:193], v[2:17]
	ds_write_b128 v144, v[146:149] offset:18432
	s_setprio 0
	s_cmp_lt_u32 s3, 14
	s_waitcnt lgkmcnt(0)
	s_barrier
	s_branch .LBB0_12
; #define G_STORE(ST, S, unused) do { char* d_ = smem + (ST) * STAGE; \
;     *(uint4*)(d_ + alo[0]) = S##a0; *(uint4*)(d_ + alo[1]) = S##a1; *(uint4*)(d_ + alo[2]) = S##a2; *(uint4*)(d_ + alo[3]) = S##a3; \
;     *(uint4*)(d_ + blo[0]) = S##b0; *(uint4*)(d_ + blo[1]) = S##b1; \
;     if (NBCH == 4) { *(uint4*)(d_ + blo[NBCH - 2]) = S##b2; *(uint4*)(d_ + blo[NBCH - 1]) = S##b3; } } while (0)
; template <int NJ, class RowA>
; DI void gemm_main(f32x16 (&acc)[2][NJ], const bf16_t* __restrict__ A, RowA rowA, size_t kstrideA, int m0, int Mmax,
;                   const bf16_t* __restrict__ Bt, size_t ldb, int n0, int nk, char* smem) {
;     ...
;   __syncthreads();
;   G_LOAD(x0, 0, 0);
;   G_LOAD(x1, 0, 1);
;   G_STORE(0, x0, 0);
;   __syncthreads();
; #pragma unroll 1
;   for (int kt = 0; kt < nk; kt += 2) {
;     G_LOAD(x0, 0, (kt + 2 < nk ? kt + 2 : nk - 1));
;     G_COMPUTE(0);
;     G_STORE(1, x1, 0);
;     __syncthreads();
;     G_LOAD(x1, 0, (kt + 3 < nk ? kt + 3 : nk - 1));
;     G_COMPUTE(1);
;     G_STORE(0, x0, 0);
;     __syncthreads();
;   }
.Lpeel_tail_12:
	ds_read_b128 v[166:169], v0
	ds_read_b128 v[170:173], v139 offset:18432
	ds_read_b128 v[174:177], v139 offset:23040
	ds_read_b128 v[178:181], v0 offset:4608
	s_add_i32 s4, s3, 4
	s_min_u32 s4, s4, 15
	s_lshl_b32 s14, s4, 7
	v_lshl_add_u64 v[98:99], v[122:123], 0, s[14:15]
	v_lshl_add_u64 v[102:103], v[124:125], 0, s[14:15]
	v_lshl_add_u64 v[106:107], v[126:127], 0, s[14:15]
	v_lshl_add_u64 v[110:111], v[128:129], 0, s[14:15]
	v_lshl_add_u64 v[114:115], v[130:131], 0, s[14:15]
	v_lshl_add_u64 v[118:119], v[132:133], 0, s[14:15]
	s_add_i32 s3, s3, 2
	v_lshl_add_u64 v[158:159], v[134:135], 0, s[14:15]
	v_lshl_add_u64 v[160:161], v[136:137], 0, s[14:15]
	s_setprio 1
	ds_read_b128 v[182:185], v0 offset:32
	ds_read_b128 v[186:189], v139 offset:18464
	ds_read_b128 v[190:193], v139 offset:23072
	ds_read_b128 v[194:197], v0 offset:4640
	s_waitcnt lgkmcnt(4)
	v_mfma_f32_32x32x16_bf16 v[50:65], v[166:169], v[170:173], v[50:65]
	v_mfma_f32_32x32x16_bf16 v[34:49], v[166:169], v[174:177], v[34:49]
	v_mfma_f32_32x32x16_bf16 v[18:33], v[178:181], v[170:173], v[18:33]
	v_mfma_f32_32x32x16_bf16 v[2:17], v[178:181], v[174:177], v[2:17]
	ds_read_b128 v[166:169], v0 offset:64
	ds_read_b128 v[170:173], v139 offset:18496
	ds_read_b128 v[174:177], v139 offset:23104
	ds_read_b128 v[178:181], v0 offset:4672
	s_waitcnt lgkmcnt(4)
	v_mfma_f32_32x32x16_bf16 v[50:65], v[182:185], v[186:189], v[50:65]
	v_mfma_f32_32x32x16_bf16 v[34:49], v[182:185], v[190:193], v[34:49]
	v_mfma_f32_32x32x16_bf16 v[18:33], v[194:197], v[186:189], v[18:33]
	v_mfma_f32_32x32x16_bf16 v[2:17], v[194:197], v[190:193], v[2:17]
	ds_read_b128 v[182:185], v0 offset:96
	ds_read_b128 v[186:189], v139 offset:18528
	ds_read_b128 v[190:193], v139 offset:23136
	ds_read_b128 v[194:197], v0 offset:4704
	s_waitcnt lgkmcnt(4)
	v_mfma_f32_32x32x16_bf16 v[50:65], v[166:169], v[170:173], v[50:65]
	s_waitcnt vmcnt(0)
	ds_write_b128 v138, v[78:81] offset:36864
	v_mfma_f32_32x32x16_bf16 v[34:49], v[166:169], v[174:177], v[34:49]
	ds_write_b128 v140, v[86:89] offset:36864
	v_mfma_f32_32x32x16_bf16 v[18:33], v[178:181], v[170:173], v[18:33]
	ds_write_b128 v142, v[90:93] offset:36864
	v_mfma_f32_32x32x16_bf16 v[2:17], v[178:181], v[174:177], v[2:17]
	ds_write_b128 v144, v[94:97] offset:36864
	s_waitcnt lgkmcnt(4)
	v_mfma_f32_32x32x16_bf16 v[50:65], v[182:185], v[186:189], v[50:65]
	ds_write_b128 v138, v[74:77] offset:55296
	v_mfma_f32_32x32x16_bf16 v[34:49], v[182:185], v[190:193], v[34:49]
	ds_write_b128 v140, v[82:85] offset:55296
	v_mfma_f32_32x32x16_bf16 v[18:33], v[194:197], v[186:189], v[18:33]
	ds_write_b128 v142, v[66:69] offset:55296
	v_mfma_f32_32x32x16_bf16 v[2:17], v[194:197], v[190:193], v[2:17]
	ds_write_b128 v144, v[70:73] offset:55296
	s_setprio 0
	s_min_u32 s4, s3, 12
	s_lshl_b32 s14, s4, 7
	v_lshl_add_u64 v[66:67], v[122:123], 0, s[14:15]
	v_lshl_add_u64 v[68:69], v[124:125], 0, s[14:15]
	v_lshl_add_u64 v[70:71], v[126:127], 0, s[14:15]
	v_lshl_add_u64 v[72:73], v[128:129], 0, s[14:15]
	v_lshl_add_u64 v[74:75], v[130:131], 0, s[14:15]
	v_lshl_add_u64 v[82:83], v[132:133], 0, s[14:15]
	s_waitcnt lgkmcnt(0)
	s_barrier
	ds_read_b128 v[166:169], v0 offset:36864
	ds_read_b128 v[170:173], v139 offset:55296
	ds_read_b128 v[174:177], v139 offset:59904
	ds_read_b128 v[178:181], v0 offset:41472
	v_lshl_add_u64 v[154:155], v[134:135], 0, s[14:15]
	v_lshl_add_u64 v[156:157], v[136:137], 0, s[14:15]
	s_setprio 1
	ds_read_b128 v[182:185], v0 offset:36896
	ds_read_b128 v[186:189], v139 offset:55328
	ds_read_b128 v[190:193], v139 offset:59936
	ds_read_b128 v[194:197], v0 offset:41504
	s_waitcnt lgkmcnt(4)
	v_mfma_f32_32x32x16_bf16 v[50:65], v[166:169], v[170:173], v[50:65]
	v_mfma_f32_32x32x16_bf16 v[34:49], v[166:169], v[174:177], v[34:49]
	v_mfma_f32_32x32x16_bf16 v[18:33], v[178:181], v[170:173], v[18:33]
	v_mfma_f32_32x32x16_bf16 v[2:17], v[178:181], v[174:177], v[2:17]
	ds_read_b128 v[166:169], v0 offset:36928
	ds_read_b128 v[170:173], v139 offset:55360
	ds_read_b128 v[174:177], v139 offset:59968
	ds_read_b128 v[178:181], v0 offset:41536
	s_waitcnt lgkmcnt(4)
	v_mfma_f32_32x32x16_bf16 v[50:65], v[182:185], v[186:189], v[50:65]
	v_mfma_f32_32x32x16_bf16 v[34:49], v[182:185], v[190:193], v[34:49]
	v_mfma_f32_32x32x16_bf16 v[18:33], v[194:197], v[186:189], v[18:33]
	v_mfma_f32_32x32x16_bf16 v[2:17], v[194:197], v[190:193], v[2:17]
	ds_read_b128 v[182:185], v0 offset:36960
	ds_read_b128 v[186:189], v139 offset:55392
	ds_read_b128 v[190:193], v139 offset:60000
	ds_read_b128 v[194:197], v0 offset:41568
	s_waitcnt lgkmcnt(4)
	v_mfma_f32_32x32x16_bf16 v[50:65], v[166:169], v[170:173], v[50:65]
	v_mfma_f32_32x32x16_bf16 v[34:49], v[166:169], v[174:177], v[34:49]
	v_mfma_f32_32x32x16_bf16 v[18:33], v[178:181], v[170:173], v[18:33]
	v_mfma_f32_32x32x16_bf16 v[2:17], v[178:181], v[174:177], v[2:17]
	s_waitcnt lgkmcnt(0)
	v_mfma_f32_32x32x16_bf16 v[50:65], v[182:185], v[186:189], v[50:65]
	v_mfma_f32_32x32x16_bf16 v[34:49], v[182:185], v[190:193], v[34:49]
	v_mfma_f32_32x32x16_bf16 v[18:33], v[194:197], v[186:189], v[18:33]
	v_mfma_f32_32x32x16_bf16 v[2:17], v[194:197], v[190:193], v[2:17]
	s_setprio 0
	s_cmp_lt_u32 s3, 14
	s_waitcnt lgkmcnt(0)
	s_barrier
; #define TIDX (tid_launder())
; DI int crow(int reg, int hh) { return (reg & 3) + 8 * (reg >> 2) + 4 * hh; }
; template <int NJ>
; DI void acc_to_ct(const f32x16 (&acc)[2][NJ], float* Ct) {
;   const int lane = TIDX & 63, wid = TIDX >> 6, wm = wid >> 1, wn = wid & 1;
;   const int r = lane & 31, hh = lane >> 5;
; #pragma unroll
;   for (int i = 0; i < 2; ++i)
; #pragma unroll
;     for (int j = 0; j < NJ; ++j)
; #pragma unroll
;       for (int e = 0; e < 16; ++e) Ct[(wm * 64 + i * 32 + crow(e, hh)) * 132 + wn * 32 * NJ + j * 32 + r] = acc[i][j][e];
;   __syncthreads();
; DI void outproj_tile(const Params& p, int l, int mt, int tn, char* smem) {
;     ...
;     const int tid = TIDX, c = (tid & 31) * 4, row0 = tid >> 5;
;     float4 xa[16];
; #pragma unroll
;     for (int q = 0; q < 16; ++q) xa[q] = *(const float4*)(xo + (size_t)(m0 + row0 + 8 * q) * 1024 + tn * 128 + c);
	v_mov_b32_e32 v0, v230
	s_waitcnt vmcnt(1)
	v_mov_b32_e32 v66, v230
	v_and_b32_e32 v67, 31, v0
	v_lshrrev_b32_e32 v0, 3, v0
	v_and_b32_e32 v0, 4, v0
	v_lshrrev_b32_e32 v68, 1, v66
	v_and_or_b32 v0, v68, s47, v0
	v_and_or_b32 v66, v66, 64, v67
	v_mul_lo_u32 v0, v0, s79
	v_lshl_add_u32 v0, v66, 2, v0
	ds_write2_b32 v0, v50, v34 offset1:32
	ds_write2_b32 v0, v51, v35 offset0:132 offset1:164
	v_add_u32_e32 v34, 0x400, v0
	ds_write2_b32 v34, v52, v36 offset0:8 offset1:40
	ds_write2_b32 v34, v53, v37 offset0:140 offset1:172
	v_add_u32_e32 v34, 0x1000, v0
	ds_write2_b32 v34, v54, v38 offset0:32 offset1:64
	ds_write2_b32 v34, v55, v39 offset0:164 offset1:196
	v_add_u32_e32 v34, 0x1400, v0
	ds_write2_b32 v34, v56, v40 offset0:40 offset1:72
	ds_write2_b32 v34, v57, v41 offset0:172 offset1:204
	v_add_u32_e32 v34, 0x2000, v0
	ds_write2_b32 v34, v58, v42 offset0:64 offset1:96
	ds_write2_b32 v34, v59, v43 offset0:196 offset1:228
	v_add_u32_e32 v34, 0x2400, v0
	ds_write2_b32 v34, v60, v44 offset0:72 offset1:104
	ds_write2_b32 v34, v61, v45 offset0:204 offset1:236
	v_add_u32_e32 v34, 0x3000, v0
	ds_write2_b32 v34, v62, v46 offset0:96 offset1:128
	v_add_u32_e32 v34, 0x3200, v0
	ds_write2_b32 v34, v63, v47 offset0:100 offset1:132
	v_add_u32_e32 v34, 0x3400, v0
	ds_write2_b32 v34, v64, v48 offset0:104 offset1:136
	v_add_u32_e32 v34, 0x3600, v0
	ds_write2_b32 v34, v65, v49 offset0:108 offset1:140
	v_add_u32_e32 v34, 0x4000, v0
	ds_write2_b32 v34, v18, v2 offset0:128 offset1:160
	v_add_u32_e32 v2, 0x4400, v0
	ds_write2_b32 v2, v19, v3 offset0:4 offset1:36
	ds_write2_b32 v2, v20, v4 offset0:136 offset1:168
	v_add_u32_e32 v2, 0x4800, v0
	ds_write2_b32 v2, v21, v5 offset0:12 offset1:44
	v_add_u32_e32 v2, 0x5000, v0
	ds_write2_b32 v2, v22, v6 offset0:160 offset1:192
	v_add_u32_e32 v2, 0x5400, v0
	ds_write2_b32 v2, v23, v7 offset0:36 offset1:68
	ds_write2_b32 v2, v24, v8 offset0:168 offset1:200
	v_add_u32_e32 v2, 0x5800, v0
	ds_write2_b32 v2, v25, v9 offset0:44 offset1:76
	v_add_u32_e32 v2, 0x6000, v0
	ds_write2_b32 v2, v26, v10 offset0:192 offset1:224
	v_add_u32_e32 v2, 0x6400, v0
	ds_write2_b32 v2, v27, v11 offset0:68 offset1:100
	ds_write2_b32 v2, v28, v12 offset0:200 offset1:232
	v_add_u32_e32 v2, 0x6800, v0
	ds_write2_b32 v2, v29, v13 offset0:76 offset1:108
	v_add_u32_e32 v2, 0x7200, v0
	ds_write2_b32 v2, v30, v14 offset0:96 offset1:128
	v_add_u32_e32 v2, 0x7400, v0
	ds_write2_b32 v2, v31, v15 offset0:100 offset1:132
	v_add_u32_e32 v2, 0x7600, v0
	v_add_u32_e32 v0, 0x7800, v0
	ds_write2_b32 v0, v33, v17 offset0:108 offset1:140
	v_mov_b32_e32 v0, v230
	ds_write2_b32 v2, v32, v16 offset0:104 offset1:136
	s_waitcnt lgkmcnt(0)
	s_barrier
	s_lshl_b32 s14, s2, 2
	v_ashrrev_i32_e32 v68, 5, v0
	v_readlane_b32 s2, v254, 3
	v_add_u32_e32 v2, s1, v68
	v_readlane_b32 s3, v254, 4
	s_add_u32 s2, s2, s14
	v_lshlrev_b32_e32 v0, 4, v0
	s_addc_u32 s3, s3, 0
	v_and_b32_e32 v0, 0x1f0, v0
	v_ashrrev_i32_e32 v3, 31, v2
	v_lshl_add_u64 v[4:5], s[2:3], 0, v[0:1]
	v_lshlrev_b64 v[8:9], 12, v[2:3]
	s_mov_b64 s[2:3], 0x18000
	v_lshl_add_u64 v[20:21], v[8:9], 0, s[2:3]
	s_mov_b64 s[2:3], 0x20000
	v_lshl_add_u64 v[24:25], v[8:9], 0, s[2:3]
	s_mov_b64 s[2:3], 0x28000
	v_lshl_add_u64 v[28:29], v[8:9], 0, s[2:3]
	s_mov_b64 s[2:3], 0x30000
	v_lshl_add_u64 v[32:33], v[8:9], 0, s[2:3]
	s_mov_b64 s[2:3], 0x38000
	v_lshl_add_u64 v[36:37], v[8:9], 0, s[2:3]
	s_mov_b64 s[2:3], 0x40000
	v_lshl_add_u64 v[40:41], v[8:9], 0, s[2:3]
	s_mov_b64 s[2:3], 0x48000
	v_lshl_add_u64 v[44:45], v[8:9], 0, s[2:3]
	s_mov_b64 s[2:3], 0x50000
	v_lshl_add_u64 v[48:49], v[8:9], 0, s[2:3]
	s_mov_b64 s[2:3], 0x58000
	v_lshl_add_u64 v[52:53], v[8:9], 0, s[2:3]
	s_mov_b64 s[2:3], 0x60000
	v_lshl_add_u64 v[56:57], v[8:9], 0, s[2:3]
	s_mov_b64 s[2:3], 0x68000
	v_lshl_add_u64 v[60:61], v[8:9], 0, s[2:3]
	s_mov_b64 s[2:3], 0x70000
	v_lshl_add_u64 v[64:65], v[8:9], 0, s[2:3]
	s_mov_b64 s[2:3], 0x78000
	v_readlane_b32 s16, v252, 9
	v_lshl_add_u64 v[12:13], v[8:9], 0, s[48:49]
	v_lshl_add_u64 v[16:17], v[8:9], 0, s[40:41]
	v_lshl_add_u64 v[66:67], v[8:9], 0, s[2:3]
	v_readlane_b32 s22, v252, 15
	v_readlane_b32 s23, v252, 16
	v_lshl_add_u64 v[62:63], v[4:5], 0, v[8:9]
	v_lshl_add_u64 v[58:59], v[4:5], 0, v[12:13]
	v_lshl_add_u64 v[54:55], v[4:5], 0, v[16:17]
	v_lshl_add_u64 v[50:51], v[4:5], 0, v[20:21]
	v_lshl_add_u64 v[46:47], v[4:5], 0, v[24:25]
	v_lshl_add_u64 v[42:43], v[4:5], 0, v[28:29]
	v_lshl_add_u64 v[38:39], v[4:5], 0, v[32:33]
	v_lshl_add_u64 v[34:35], v[4:5], 0, v[36:37]
	v_lshl_add_u64 v[30:31], v[4:5], 0, v[40:41]
	v_lshl_add_u64 v[26:27], v[4:5], 0, v[44:45]
	v_lshl_add_u64 v[22:23], v[4:5], 0, v[48:49]
	v_lshl_add_u64 v[18:19], v[4:5], 0, v[52:53]
	v_lshl_add_u64 v[14:15], v[4:5], 0, v[56:57]
	v_lshl_add_u64 v[10:11], v[4:5], 0, v[60:61]
	v_lshl_add_u64 v[6:7], v[4:5], 0, v[64:65]
	v_lshl_add_u64 v[2:3], v[4:5], 0, v[66:67]
	v_lshl_add_u64 v[4:5], s[22:23], 0, v[8:9]
	v_lshl_add_u64 v[4:5], v[4:5], 0, s[14:15]
	v_lshl_add_u64 v[96:97], v[4:5], 0, v[0:1]
	v_lshl_add_u64 v[4:5], s[22:23], 0, v[12:13]
	v_lshl_add_u64 v[4:5], v[4:5], 0, s[14:15]
	v_lshl_add_u64 v[94:95], v[4:5], 0, v[0:1]
	v_lshl_add_u64 v[4:5], s[22:23], 0, v[16:17]
	v_lshl_add_u64 v[4:5], v[4:5], 0, s[14:15]
	v_lshl_add_u64 v[92:93], v[4:5], 0, v[0:1]
	v_lshl_add_u64 v[4:5], s[22:23], 0, v[20:21]
	v_lshl_add_u64 v[4:5], v[4:5], 0, s[14:15]
	v_lshl_add_u64 v[90:91], v[4:5], 0, v[0:1]
	v_lshl_add_u64 v[4:5], s[22:23], 0, v[24:25]
	v_lshl_add_u64 v[4:5], v[4:5], 0, s[14:15]
	v_lshl_add_u64 v[88:89], v[4:5], 0, v[0:1]
	v_lshl_add_u64 v[4:5], s[22:23], 0, v[28:29]
	v_lshl_add_u64 v[4:5], v[4:5], 0, s[14:15]
	v_lshl_add_u64 v[86:87], v[4:5], 0, v[0:1]
	v_lshl_add_u64 v[4:5], s[22:23], 0, v[32:33]
	v_lshl_add_u64 v[4:5], v[4:5], 0, s[14:15]
	v_lshl_add_u64 v[84:85], v[4:5], 0, v[0:1]
	v_lshl_add_u64 v[4:5], s[22:23], 0, v[36:37]
	v_lshl_add_u64 v[4:5], v[4:5], 0, s[14:15]
	v_lshl_add_u64 v[82:83], v[4:5], 0, v[0:1]
	v_lshl_add_u64 v[4:5], s[22:23], 0, v[40:41]
	v_lshl_add_u64 v[4:5], v[4:5], 0, s[14:15]
	v_lshl_add_u64 v[80:81], v[4:5], 0, v[0:1]
	v_lshl_add_u64 v[4:5], s[22:23], 0, v[44:45]
	v_lshl_add_u64 v[4:5], v[4:5], 0, s[14:15]
	v_lshl_add_u64 v[78:79], v[4:5], 0, v[0:1]
	v_lshl_add_u64 v[4:5], s[22:23], 0, v[48:49]
	v_lshl_add_u64 v[4:5], v[4:5], 0, s[14:15]
	v_lshl_add_u64 v[76:77], v[4:5], 0, v[0:1]
	v_lshl_add_u64 v[4:5], s[22:23], 0, v[52:53]
	v_lshl_add_u64 v[4:5], v[4:5], 0, s[14:15]
	v_lshl_add_u64 v[74:75], v[4:5], 0, v[0:1]
	v_lshl_add_u64 v[4:5], s[22:23], 0, v[56:57]
	v_lshl_add_u64 v[4:5], v[4:5], 0, s[14:15]
	s_waitcnt vmcnt(0)
; #define TIDX (tid_launder())
; DI void outproj_tile(const Params& p, int l, int mt, int tn, char* smem) {
;     ...
;     const int tid = TIDX, c = (tid & 31) * 4, row0 = tid >> 5;
;     float4 xa[16];
; #pragma unroll
;     for (int q = 0; q < 16; ++q) xa[q] = *(const float4*)(xo + (size_t)(m0 + row0 + 8 * q) * 1024 + tn * 128 + c);
; #pragma unroll
;     for (int q = 0; q < 16; ++q) {
;       const float4 cc = *(const float4*)(Ct + (row0 + 8 * q) * 132 + c);
;       *(float4*)(p.out + (size_t)(m0 + row0 + 8 * q) * 1024 + tn * 128 + c) = make_float4(xa[q].x + cc.x, xa[q].y + cc.y, xa[q].z + cc.z, xa[q].w + cc.w);
;     }
;   }
;   __syncthreads();
; __global__ void __launch_bounds__(256, 2) mega(Params p, int ph_lo, int ph_hi) {
;     ...
;         for (int idx = blockIdx.x >> 3; idx < 256; idx += gridDim.x >> 3) { const int t = (blockIdx.x & 7) * 256 + idx; outproj_tile(p, l, t >> 3, t & 7, smem); }
	v_lshl_add_u64 v[72:73], v[4:5], 0, v[0:1]
	v_lshl_add_u64 v[4:5], s[22:23], 0, v[60:61]
	v_lshl_add_u64 v[4:5], v[4:5], 0, s[14:15]
	v_lshl_add_u64 v[70:71], v[4:5], 0, v[0:1]
	v_lshl_add_u64 v[4:5], s[22:23], 0, v[64:65]
	v_lshl_add_u64 v[4:5], v[4:5], 0, s[14:15]
	v_mad_u64_u32 v[98:99], s[2:3], v68, s79, v[0:1]
	v_lshl_add_u64 v[68:69], v[4:5], 0, v[0:1]
	v_lshl_add_u64 v[4:5], s[22:23], 0, v[66:67]
	v_lshl_add_u64 v[4:5], v[4:5], 0, s[14:15]
	v_lshl_add_u64 v[66:67], v[4:5], 0, v[0:1]
	global_load_dwordx4 v[2:5], v[2:3], off
	ds_read_b128 v[100:103], v98 offset:63360
	global_load_dwordx4 v[6:9], v[6:7], off
	v_readlane_b32 s1, v250, 60
	global_load_dwordx4 v[10:13], v[10:11], off
	s_add_i32 s0, s0, s1
	global_load_dwordx4 v[14:17], v[14:15], off
	s_cmpk_gt_u32 s0, 0xff
	global_load_dwordx4 v[18:21], v[18:19], off
	v_readlane_b32 s17, v252, 10
	global_load_dwordx4 v[22:25], v[22:23], off
	v_readlane_b32 s18, v252, 11
	global_load_dwordx4 v[26:29], v[26:27], off
	v_readlane_b32 s19, v252, 12
	global_load_dwordx4 v[30:33], v[30:31], off
	v_readlane_b32 s20, v252, 13
	global_load_dwordx4 v[34:37], v[34:35], off
	v_readlane_b32 s21, v252, 14
	global_load_dwordx4 v[38:41], v[38:39], off
	v_readlane_b32 s24, v252, 17
	global_load_dwordx4 v[42:45], v[42:43], off
	v_readlane_b32 s25, v252, 18
	global_load_dwordx4 v[46:49], v[46:47], off
	v_readlane_b32 s26, v252, 19
	global_load_dwordx4 v[50:53], v[50:51], off
	v_readlane_b32 s27, v252, 20
	global_load_dwordx4 v[54:57], v[54:55], off
	v_readlane_b32 s28, v252, 21
	global_load_dwordx4 v[58:61], v[58:59], off
	v_readlane_b32 s29, v252, 22
	global_load_dwordx4 v[62:65], v[62:63], off
	v_readlane_b32 s30, v252, 23
	v_readlane_b32 s31, v252, 24
	s_waitcnt vmcnt(15) lgkmcnt(0)
	v_pk_add_f32 v[2:3], v[2:3], v[100:101]
	v_pk_add_f32 v[4:5], v[4:5], v[102:103]
	ds_read_b128 v[100:103], v98 offset:59136
	s_waitcnt vmcnt(14) lgkmcnt(0)
	v_pk_add_f32 v[6:7], v[6:7], v[100:101]
	v_pk_add_f32 v[8:9], v[8:9], v[102:103]
	ds_read_b128 v[100:103], v98 offset:54912
	s_waitcnt vmcnt(13) lgkmcnt(0)
	v_pk_add_f32 v[10:11], v[10:11], v[100:101]
	v_pk_add_f32 v[12:13], v[12:13], v[102:103]
	ds_read_b128 v[100:103], v98 offset:50688
	s_waitcnt vmcnt(12) lgkmcnt(0)
	v_pk_add_f32 v[14:15], v[14:15], v[100:101]
	v_pk_add_f32 v[16:17], v[16:17], v[102:103]
	ds_read_b128 v[100:103], v98 offset:46464
	s_waitcnt vmcnt(11) lgkmcnt(0)
	v_pk_add_f32 v[18:19], v[18:19], v[100:101]
	v_pk_add_f32 v[20:21], v[20:21], v[102:103]
	ds_read_b128 v[100:103], v98 offset:42240
	s_waitcnt vmcnt(10) lgkmcnt(0)
	v_pk_add_f32 v[22:23], v[22:23], v[100:101]
	v_pk_add_f32 v[24:25], v[24:25], v[102:103]
	ds_read_b128 v[100:103], v98 offset:38016
	s_waitcnt vmcnt(9) lgkmcnt(0)
	v_pk_add_f32 v[26:27], v[26:27], v[100:101]
	v_pk_add_f32 v[28:29], v[28:29], v[102:103]
	ds_read_b128 v[100:103], v98 offset:33792
	s_waitcnt vmcnt(8) lgkmcnt(0)
	v_pk_add_f32 v[30:31], v[30:31], v[100:101]
	v_pk_add_f32 v[32:33], v[32:33], v[102:103]
	ds_read_b128 v[100:103], v98 offset:29568
	s_waitcnt vmcnt(7) lgkmcnt(0)
	v_pk_add_f32 v[34:35], v[34:35], v[100:101]
	v_pk_add_f32 v[36:37], v[36:37], v[102:103]
	ds_read_b128 v[100:103], v98 offset:25344
	s_waitcnt vmcnt(6) lgkmcnt(0)
	v_pk_add_f32 v[38:39], v[38:39], v[100:101]
	v_pk_add_f32 v[40:41], v[40:41], v[102:103]
	ds_read_b128 v[100:103], v98 offset:21120
	s_waitcnt vmcnt(5) lgkmcnt(0)
	v_pk_add_f32 v[42:43], v[42:43], v[100:101]
	v_pk_add_f32 v[44:45], v[44:45], v[102:103]
	ds_read_b128 v[100:103], v98 offset:16896
	s_waitcnt vmcnt(4) lgkmcnt(0)
	v_pk_add_f32 v[46:47], v[46:47], v[100:101]
	v_pk_add_f32 v[48:49], v[48:49], v[102:103]
	ds_read_b128 v[100:103], v98 offset:12672
	s_waitcnt vmcnt(3) lgkmcnt(0)
	v_pk_add_f32 v[50:51], v[50:51], v[100:101]
	v_pk_add_f32 v[52:53], v[52:53], v[102:103]
	ds_read_b128 v[100:103], v98 offset:8448
	s_waitcnt vmcnt(2) lgkmcnt(0)
	v_pk_add_f32 v[54:55], v[54:55], v[100:101]
	v_pk_add_f32 v[56:57], v[56:57], v[102:103]
	ds_read_b128 v[100:103], v98 offset:4224
	s_waitcnt vmcnt(1) lgkmcnt(0)
	v_pk_add_f32 v[58:59], v[58:59], v[100:101]
	ds_read_b128 v[98:101], v98
	v_pk_add_f32 v[60:61], v[60:61], v[102:103]
	s_waitcnt vmcnt(0) lgkmcnt(0)
	v_pk_add_f32 v[62:63], v[62:63], v[98:99]
	v_pk_add_f32 v[64:65], v[64:65], v[100:101]
	global_store_dwordx4 v[96:97], v[62:65], off
	global_store_dwordx4 v[94:95], v[58:61], off
	global_store_dwordx4 v[92:93], v[54:57], off
	global_store_dwordx4 v[90:91], v[50:53], off
	global_store_dwordx4 v[88:89], v[46:49], off
	global_store_dwordx4 v[86:87], v[42:45], off
	global_store_dwordx4 v[84:85], v[38:41], off
	global_store_dwordx4 v[82:83], v[34:37], off
	global_store_dwordx4 v[80:81], v[30:33], off
	global_store_dwordx4 v[78:79], v[26:29], off
	global_store_dwordx4 v[76:77], v[22:25], off
	global_store_dwordx4 v[74:75], v[18:21], off
	global_store_dwordx4 v[72:73], v[14:17], off
	global_store_dwordx4 v[70:71], v[10:13], off
	global_store_dwordx4 v[68:69], v[6:9], off
	global_store_dwordx4 v[66:67], v[2:5], off
	s_barrier
	s_cbranch_scc0 .LBB0_11

; #define G_STORE(ST, S, unused) do { char* d_ = smem + (ST) * STAGE; \
;     *(uint4*)(d_ + alo[0]) = S##a0; *(uint4*)(d_ + alo[1]) = S##a1; *(uint4*)(d_ + alo[2]) = S##a2; *(uint4*)(d_ + alo[3]) = S##a3; \
;     *(uint4*)(d_ + blo[0]) = S##b0; *(uint4*)(d_ + blo[1]) = S##b1; \
;     if (NBCH == 4) { *(uint4*)(d_ + blo[NBCH - 2]) = S##b2; *(uint4*)(d_ + blo[NBCH - 1]) = S##b3; } } while (0)
; template <int NJ, class RowA>
; DI void gemm_main(f32x16 (&acc)[2][NJ], const bf16_t* __restrict__ A, RowA rowA, size_t kstrideA, int m0, int Mmax,
;                   const bf16_t* __restrict__ Bt, size_t ldb, int n0, int nk, char* smem) {
;     ...
;   __syncthreads();
;   G_LOAD(x0, 0, 0);
;   G_LOAD(x1, 0, 1);
;   G_STORE(0, x0, 0);
;   __syncthreads();
; #pragma unroll 1
;   for (int kt = 0; kt < nk; kt += 2) {
;     G_LOAD(x0, 0, (kt + 2 < nk ? kt + 2 : nk - 1));
;     G_COMPUTE(0);
;     G_STORE(1, x1, 0);
;     __syncthreads();
;     G_LOAD(x1, 0, (kt + 3 < nk ? kt + 3 : nk - 1));
;     G_COMPUTE(1);
;     G_STORE(0, x0, 0);
;     __syncthreads();
;   }
; DI void merge_tile(const Params& p, int mt, int nt, char* smem) {
;     ...
;     gemm_main<1>(ag, p.h, RowLin{1024}, 64, m0, T_TOK, p.wt_in + (size_t)(4224 + x * 1024) * 1024, 1024, n0, 16, smem);
.LBB0_19:
	s_cmp_lt_i32 s4, 12
	s_cbranch_scc0 .Lpeel_tail_19
	ds_read_b128 v[176:179], v0
	ds_read_b128 v[180:183], v71 offset:18432
	ds_read_b128 v[184:187], v0 offset:4608
	s_add_i32 s5, s4, 4
	s_min_u32 s5, s5, 15
	s_lshl_b32 s14, s5, 7
	v_lshl_add_u64 v[78:79], v[58:59], 0, s[14:15]
	v_lshl_add_u64 v[82:83], v[60:61], 0, s[14:15]
	v_lshl_add_u64 v[86:87], v[62:63], 0, s[14:15]
	v_lshl_add_u64 v[122:123], v[64:65], 0, s[14:15]
	v_lshl_add_u64 v[126:127], v[66:67], 0, s[14:15]
	v_lshl_add_u64 v[130:131], v[68:69], 0, s[14:15]
	s_add_i32 s4, s4, 2
	s_setprio 1
	ds_read_b128 v[188:191], v0 offset:32
	ds_read_b128 v[192:195], v71 offset:18464
	ds_read_b128 v[196:199], v0 offset:4640
	s_waitcnt lgkmcnt(3)
	v_mfma_f32_32x32x16_bf16 v[18:33], v[176:179], v[180:183], v[18:33]
	global_load_dwordx4 v[78:81], v[78:79], off
	s_nop 0
	global_load_dwordx4 v[82:85], v[82:83], off
	v_mfma_f32_32x32x16_bf16 v[2:17], v[184:187], v[180:183], v[2:17]
	global_load_dwordx4 v[86:89], v[86:87], off
	ds_read_b128 v[176:179], v0 offset:64
	ds_read_b128 v[180:183], v71 offset:18496
	ds_read_b128 v[184:187], v0 offset:4672
	s_waitcnt lgkmcnt(3)
	v_mfma_f32_32x32x16_bf16 v[18:33], v[188:191], v[192:195], v[18:33]
	global_load_dwordx4 v[122:125], v[122:123], off
	s_nop 0
	global_load_dwordx4 v[126:129], v[126:127], off
	v_mfma_f32_32x32x16_bf16 v[2:17], v[196:199], v[192:195], v[2:17]
	global_load_dwordx4 v[130:133], v[130:131], off
	ds_read_b128 v[188:191], v0 offset:96
	ds_read_b128 v[192:195], v71 offset:18528
	ds_read_b128 v[196:199], v0 offset:4704
	s_waitcnt lgkmcnt(3)
	v_mfma_f32_32x32x16_bf16 v[18:33], v[176:179], v[180:183], v[18:33]
	s_waitcnt vmcnt(6)
	ds_write_b128 v70, v[34:37] offset:27648
	ds_write_b128 v72, v[38:41] offset:27648
	v_mfma_f32_32x32x16_bf16 v[2:17], v[184:187], v[180:183], v[2:17]
	ds_write_b128 v74, v[42:45] offset:27648
	s_waitcnt lgkmcnt(3)
	v_mfma_f32_32x32x16_bf16 v[18:33], v[188:191], v[192:195], v[18:33]
	ds_write_b128 v76, v[54:57] offset:27648
	ds_write_b128 v70, v[46:49] offset:46080
	v_mfma_f32_32x32x16_bf16 v[2:17], v[196:199], v[192:195], v[2:17]
	ds_write_b128 v72, v[50:53] offset:46080
	s_setprio 0
	s_min_u32 s5, s4, 12
	s_lshl_b32 s14, s5, 7
	v_lshl_add_u64 v[34:35], v[58:59], 0, s[14:15]
	v_lshl_add_u64 v[38:39], v[60:61], 0, s[14:15]
	v_lshl_add_u64 v[42:43], v[62:63], 0, s[14:15]
	v_lshl_add_u64 v[46:47], v[64:65], 0, s[14:15]
	v_lshl_add_u64 v[48:49], v[66:67], 0, s[14:15]
	v_lshl_add_u64 v[50:51], v[68:69], 0, s[14:15]
	s_waitcnt lgkmcnt(0)
	s_barrier
	ds_read_b128 v[176:179], v0 offset:27648
	ds_read_b128 v[180:183], v71 offset:46080
	ds_read_b128 v[184:187], v0 offset:32256
	s_setprio 1
	ds_read_b128 v[188:191], v0 offset:27680
	ds_read_b128 v[192:195], v71 offset:46112
	ds_read_b128 v[196:199], v0 offset:32288
	s_waitcnt lgkmcnt(3)
	v_mfma_f32_32x32x16_bf16 v[18:33], v[176:179], v[180:183], v[18:33]
	global_load_dwordx4 v[34:37], v[34:35], off offset:384
	s_nop 0
	global_load_dwordx4 v[38:41], v[38:39], off offset:384
	v_mfma_f32_32x32x16_bf16 v[2:17], v[184:187], v[180:183], v[2:17]
	global_load_dwordx4 v[42:45], v[42:43], off offset:384
	ds_read_b128 v[176:179], v0 offset:27712
	ds_read_b128 v[180:183], v71 offset:46144
	ds_read_b128 v[184:187], v0 offset:32320
	s_waitcnt lgkmcnt(3)
	v_mfma_f32_32x32x16_bf16 v[18:33], v[188:191], v[192:195], v[18:33]
	global_load_dwordx4 v[54:57], v[46:47], off offset:384
	s_nop 0
	global_load_dwordx4 v[46:49], v[48:49], off offset:384
	v_mfma_f32_32x32x16_bf16 v[2:17], v[196:199], v[192:195], v[2:17]
	global_load_dwordx4 v[50:53], v[50:51], off offset:384
	ds_read_b128 v[188:191], v0 offset:27744
	ds_read_b128 v[192:195], v71 offset:46176
	ds_read_b128 v[196:199], v0 offset:32352
	s_waitcnt lgkmcnt(3)
	v_mfma_f32_32x32x16_bf16 v[18:33], v[176:179], v[180:183], v[18:33]
	s_waitcnt vmcnt(6)
	ds_write_b128 v70, v[78:81]
	ds_write_b128 v72, v[82:85]
	v_mfma_f32_32x32x16_bf16 v[2:17], v[184:187], v[180:183], v[2:17]
	ds_write_b128 v74, v[86:89]
	s_waitcnt lgkmcnt(3)
	v_mfma_f32_32x32x16_bf16 v[18:33], v[188:191], v[192:195], v[18:33]
	ds_write_b128 v76, v[122:125]
	ds_write_b128 v70, v[126:129] offset:18432
	v_mfma_f32_32x32x16_bf16 v[2:17], v[196:199], v[192:195], v[2:17]
	ds_write_b128 v72, v[130:133] offset:18432
	s_setprio 0
	s_cmp_lt_u32 s4, 14
	s_waitcnt lgkmcnt(0)
	s_barrier
	s_branch .LBB0_19
; #define TIDX (tid_launder())
; #define G_STORE(ST, S, unused) do { char* d_ = smem + (ST) * STAGE; \
;     *(uint4*)(d_ + alo[0]) = S##a0; *(uint4*)(d_ + alo[1]) = S##a1; *(uint4*)(d_ + alo[2]) = S##a2; *(uint4*)(d_ + alo[3]) = S##a3; \
;     *(uint4*)(d_ + blo[0]) = S##b0; *(uint4*)(d_ + blo[1]) = S##b1; \
;     if (NBCH == 4) { *(uint4*)(d_ + blo[NBCH - 2]) = S##b2; *(uint4*)(d_ + blo[NBCH - 1]) = S##b3; } } while (0)
; template <int NJ, class RowA>
; DI void gemm_main(f32x16 (&acc)[2][NJ], const bf16_t* __restrict__ A, RowA rowA, size_t kstrideA, int m0, int Mmax,
;                   const bf16_t* __restrict__ Bt, size_t ldb, int n0, int nk, char* smem) {
;     ...
;   const int tid = TIDX, lane = tid & 63, wid = tid >> 6, wm = wid >> 1, wn = wid & 1;
;   const int r = lane & 31, hh = lane >> 5;
;   const bf16_t* ap[4]; const bf16_t* bp[NBCH]; int alo[4], blo[NBCH];
; #pragma unroll
;   for (int i = 0; i < 4; ++i) {
;     const int c = tid + 256 * i, row = c >> 3, kc = c & 7;
;     int m = m0 + row; m = m < Mmax ? m : Mmax - 1;
;     ap[i] = A + rowA(m) + kc * 8; alo[i] = row * 144 + kc * 16;
;   }
; #pragma unroll
;   for (int i = 0; i < NBCH; ++i) {
;     const int c = tid + 256 * i, row = c >> 3, kc = c & 7;
;     bp[i] = Bt + (size_t)(n0 + row) * ldb + kc * 8; blo[i] = 128 * 144 + row * 144 + kc * 16;
;     ...
;   __syncthreads();
;   G_LOAD(x0, 0, 0);
;   G_LOAD(x1, 0, 1);
;   G_STORE(0, x0, 0);
;   __syncthreads();
; #pragma unroll 1
;   for (int kt = 0; kt < nk; kt += 2) {
;     G_LOAD(x0, 0, (kt + 2 < nk ? kt + 2 : nk - 1));
;     G_COMPUTE(0);
;     G_STORE(1, x1, 0);
;     __syncthreads();
;     G_LOAD(x1, 0, (kt + 3 < nk ? kt + 3 : nk - 1));
;     G_COMPUTE(1);
;     G_STORE(0, x0, 0);
;     __syncthreads();
;   }
; DI void merge_tile(const Params& p, int mt, int nt, char* smem) {
;     ...
;     const int koff = x == 0 ? 0 : (x == 1 ? 256 : 768);
;     const int nkp = x == 1 ? 8 : 4;
;     f32x16 ag[2][1], ap[2][1];
;     gemm_main<1>(ag, p.h, RowLin{1024}, 64, m0, T_TOK, p.wt_in + (size_t)(4224 + x * 1024) * 1024, 1024, n0, 16, smem);
;     gemm_main<1>(ap, p.projZ + koff, RowLin{LDA_Z}, 64, m0, T_TOK, p.wt_br + koff, 1024, n0, nkp, smem);
.Lpeel_tail_19:
	ds_read_b128 v[176:179], v0
	ds_read_b128 v[180:183], v71 offset:18432
	ds_read_b128 v[184:187], v0 offset:4608
	s_add_i32 s5, s4, 4
	s_min_u32 s5, s5, 15
	s_lshl_b32 s14, s5, 7
	v_lshl_add_u64 v[78:79], v[58:59], 0, s[14:15]
	v_lshl_add_u64 v[82:83], v[60:61], 0, s[14:15]
	v_lshl_add_u64 v[86:87], v[62:63], 0, s[14:15]
	v_lshl_add_u64 v[122:123], v[64:65], 0, s[14:15]
	v_lshl_add_u64 v[126:127], v[66:67], 0, s[14:15]
	v_lshl_add_u64 v[130:131], v[68:69], 0, s[14:15]
	s_add_i32 s4, s4, 2
	s_setprio 1
	ds_read_b128 v[188:191], v0 offset:32
	ds_read_b128 v[192:195], v71 offset:18464
	ds_read_b128 v[196:199], v0 offset:4640
	s_waitcnt lgkmcnt(3)
	v_mfma_f32_32x32x16_bf16 v[18:33], v[176:179], v[180:183], v[18:33]
	v_mfma_f32_32x32x16_bf16 v[2:17], v[184:187], v[180:183], v[2:17]
	ds_read_b128 v[176:179], v0 offset:64
	ds_read_b128 v[180:183], v71 offset:18496
	ds_read_b128 v[184:187], v0 offset:4672
	s_waitcnt lgkmcnt(3)
	v_mfma_f32_32x32x16_bf16 v[18:33], v[188:191], v[192:195], v[18:33]
	v_mfma_f32_32x32x16_bf16 v[2:17], v[196:199], v[192:195], v[2:17]
	ds_read_b128 v[188:191], v0 offset:96
	ds_read_b128 v[192:195], v71 offset:18528
	ds_read_b128 v[196:199], v0 offset:4704
	s_waitcnt lgkmcnt(3)
	v_mfma_f32_32x32x16_bf16 v[18:33], v[176:179], v[180:183], v[18:33]
	s_waitcnt vmcnt(0)
	ds_write_b128 v70, v[34:37] offset:27648
	ds_write_b128 v72, v[38:41] offset:27648
	v_mfma_f32_32x32x16_bf16 v[2:17], v[184:187], v[180:183], v[2:17]
	ds_write_b128 v74, v[42:45] offset:27648
	s_waitcnt lgkmcnt(3)
	v_mfma_f32_32x32x16_bf16 v[18:33], v[188:191], v[192:195], v[18:33]
	ds_write_b128 v76, v[54:57] offset:27648
	ds_write_b128 v70, v[46:49] offset:46080
	v_mfma_f32_32x32x16_bf16 v[2:17], v[196:199], v[192:195], v[2:17]
	ds_write_b128 v72, v[50:53] offset:46080
	s_setprio 0
	s_min_u32 s5, s4, 12
	s_lshl_b32 s14, s5, 7
	v_lshl_add_u64 v[34:35], v[58:59], 0, s[14:15]
	v_lshl_add_u64 v[38:39], v[60:61], 0, s[14:15]
	v_lshl_add_u64 v[42:43], v[62:63], 0, s[14:15]
	v_lshl_add_u64 v[46:47], v[64:65], 0, s[14:15]
	v_lshl_add_u64 v[48:49], v[66:67], 0, s[14:15]
	v_lshl_add_u64 v[50:51], v[68:69], 0, s[14:15]
	s_waitcnt lgkmcnt(0)
	s_barrier
	ds_read_b128 v[176:179], v0 offset:27648
	ds_read_b128 v[180:183], v71 offset:46080
	ds_read_b128 v[184:187], v0 offset:32256
	s_setprio 1
	ds_read_b128 v[188:191], v0 offset:27680
	ds_read_b128 v[192:195], v71 offset:46112
	ds_read_b128 v[196:199], v0 offset:32288
	s_waitcnt lgkmcnt(3)
	v_mfma_f32_32x32x16_bf16 v[18:33], v[176:179], v[180:183], v[18:33]
	v_mfma_f32_32x32x16_bf16 v[2:17], v[184:187], v[180:183], v[2:17]
	ds_read_b128 v[176:179], v0 offset:27712
	ds_read_b128 v[180:183], v71 offset:46144
	ds_read_b128 v[184:187], v0 offset:32320
	s_waitcnt lgkmcnt(3)
	v_mfma_f32_32x32x16_bf16 v[18:33], v[188:191], v[192:195], v[18:33]
	v_mfma_f32_32x32x16_bf16 v[2:17], v[196:199], v[192:195], v[2:17]
	ds_read_b128 v[188:191], v0 offset:27744
	ds_read_b128 v[192:195], v71 offset:46176
	ds_read_b128 v[196:199], v0 offset:32352
	s_waitcnt lgkmcnt(3)
	v_mfma_f32_32x32x16_bf16 v[18:33], v[176:179], v[180:183], v[18:33]
	v_mfma_f32_32x32x16_bf16 v[2:17], v[184:187], v[180:183], v[2:17]
	s_waitcnt lgkmcnt(0)
	v_mfma_f32_32x32x16_bf16 v[18:33], v[188:191], v[192:195], v[18:33]
	v_mfma_f32_32x32x16_bf16 v[2:17], v[196:199], v[192:195], v[2:17]
	s_setprio 0
	s_cmp_lt_u32 s4, 14
	s_waitcnt lgkmcnt(0)
	s_barrier
	s_cmp_eq_u32 s3, 1
	s_cselect_b32 s5, s42, 0x300
	s_cselect_b32 s4, 8, 4
	s_cmp_lg_u32 s3, 0
	v_mov_b32_e32 v58, v230
	s_cselect_b32 s5, s5, 0
	v_readlane_b32 s16, v252, 57
	s_lshl_b32 s5, s5, 1
	v_ashrrev_i32_e32 v59, 3, v58
	v_readlane_b32 s28, v253, 5
	s_waitcnt vmcnt(5)
	v_add_u32_e32 v36, s1, v59
	v_readlane_b32 s29, v253, 6
	s_add_u32 s6, s28, s5
	v_lshlrev_b32_e32 v0, 4, v58
	v_min_i32_e32 v36, 0x7fff, v36
	s_addc_u32 s7, s29, 0
	v_and_b32_e32 v0, 0x70, v0
	v_ashrrev_i32_e32 v37, 31, v36
	v_lshl_add_u64 v[34:35], s[6:7], 0, v[0:1]
	v_lshlrev_b64 v[36:37], 11, v[36:37]
	v_lshl_add_u64 v[122:123], v[34:35], 0, v[36:37]
	v_add_u32_e32 v36, 0x100, v58
	v_ashrrev_i32_e32 v60, 3, v36
	v_add_u32_e32 v36, s1, v60
	v_min_i32_e32 v36, 0x7fff, v36
	v_ashrrev_i32_e32 v37, 31, v36
	v_lshlrev_b64 v[36:37], 11, v[36:37]
	v_lshl_add_u64 v[124:125], v[34:35], 0, v[36:37]
	v_add_u32_e32 v36, 0x200, v58
	v_ashrrev_i32_e32 v61, 3, v36
	v_add_u32_e32 v36, s1, v61
	v_min_i32_e32 v36, 0x7fff, v36
	v_ashrrev_i32_e32 v37, 31, v36
	v_lshlrev_b64 v[36:37], 11, v[36:37]
	v_lshl_add_u64 v[126:127], v[34:35], 0, v[36:37]
	v_add_u32_e32 v36, 0x300, v58
	v_ashrrev_i32_e32 v62, 3, v36
	v_add_u32_e32 v36, s1, v62
	v_min_i32_e32 v36, 0x7fff, v36
	v_ashrrev_i32_e32 v37, 31, v36
	v_lshlrev_b64 v[36:37], 11, v[36:37]
	v_readlane_b32 s17, v252, 58
	s_add_u32 s8, s16, s5
	v_lshl_add_u64 v[128:129], v[34:35], 0, v[36:37]
	v_add_u32_e32 v36, s2, v59
	s_addc_u32 s9, s17, 0
	v_ashrrev_i32_e32 v37, 31, v36
	v_lshl_add_u64 v[34:35], s[8:9], 0, v[0:1]
	v_lshlrev_b64 v[36:37], 11, v[36:37]
	v_lshl_add_u64 v[130:131], v[34:35], 0, v[36:37]
	v_add_u32_e32 v36, s2, v60
	v_ashrrev_i32_e32 v37, 31, v36
	v_lshlrev_b64 v[36:37], 11, v[36:37]
	v_lshl_add_u64 v[132:133], v[34:35], 0, v[36:37]
	s_barrier
; #define G_STORE(ST, S, unused) do { char* d_ = smem + (ST) * STAGE; \
;     *(uint4*)(d_ + alo[0]) = S##a0; *(uint4*)(d_ + alo[1]) = S##a1; *(uint4*)(d_ + alo[2]) = S##a2; *(uint4*)(d_ + alo[3]) = S##a3; \
;     *(uint4*)(d_ + blo[0]) = S##b0; *(uint4*)(d_ + blo[1]) = S##b1; \
;     if (NBCH == 4) { *(uint4*)(d_ + blo[NBCH - 2]) = S##b2; *(uint4*)(d_ + blo[NBCH - 1]) = S##b3; } } while (0)
; template <int NJ, class RowA>
; DI void gemm_main(f32x16 (&acc)[2][NJ], const bf16_t* __restrict__ A, RowA rowA, size_t kstrideA, int m0, int Mmax,
;                   const bf16_t* __restrict__ Bt, size_t ldb, int n0, int nk, char* smem) {
;     ...
;   const bf16_t* ap[4]; const bf16_t* bp[NBCH]; int alo[4], blo[NBCH];
; #pragma unroll
;   for (int i = 0; i < 4; ++i) {
;     const int c = tid + 256 * i, row = c >> 3, kc = c & 7;
;     int m = m0 + row; m = m < Mmax ? m : Mmax - 1;
;     ap[i] = A + rowA(m) + kc * 8; alo[i] = row * 144 + kc * 16;
;   }
; #pragma unroll
;   for (int i = 0; i < NBCH; ++i) {
;     const int c = tid + 256 * i, row = c >> 3, kc = c & 7;
;     bp[i] = Bt + (size_t)(n0 + row) * ldb + kc * 8; blo[i] = 128 * 144 + row * 144 + kc * 16;
;   }
; #pragma unroll
;   for (int i = 0; i < 2; ++i)
; #pragma unroll
;     for (int j = 0; j < NJ; ++j)
; #pragma unroll
;       for (int e = 0; e < 16; ++e) acc[i][j][e] = 0.f;
;   uint4 x0a0, x0a1, x0a2, x0a3, x0b0, x0b1, x0b2, x0b3, x1a0, x1a1, x1a2, x1a3, x1b0, x1b1, x1b2, x1b3;
;   x0b2 = x0b3 = x1b2 = x1b3 = make_uint4(0, 0, 0, 0);
;     ...
;   __syncthreads();
;   G_LOAD(x0, 0, 0);
;   G_LOAD(x1, 0, 1);
;   G_STORE(0, x0, 0);
;   __syncthreads();
; #pragma unroll 1
;   for (int kt = 0; kt < nk; kt += 2) {
;     G_LOAD(x0, 0, (kt + 2 < nk ? kt + 2 : nk - 1));
;     G_COMPUTE(0);
;     G_STORE(1, x1, 0);
;     __syncthreads();
;     G_LOAD(x1, 0, (kt + 3 < nk ? kt + 3 : nk - 1));
;     G_COMPUTE(1);
;     G_STORE(0, x0, 0);
;     __syncthreads();
;   }
	global_load_dwordx4 v[34:37], v[122:123], off
	global_load_dwordx4 v[38:41], v[124:125], off
	global_load_dwordx4 v[42:45], v[126:127], off
	global_load_dwordx4 v[46:49], v[128:129], off
	global_load_dwordx4 v[50:53], v[130:131], off
	global_load_dwordx4 v[54:57], v[132:133], off
	global_load_dwordx4 v[66:69], v[122:123], off offset:128
	global_load_dwordx4 v[70:73], v[124:125], off offset:128
	global_load_dwordx4 v[74:77], v[126:127], off offset:128
	global_load_dwordx4 v[78:81], v[128:129], off offset:128
	global_load_dwordx4 v[82:85], v[130:131], off offset:128
	global_load_dwordx4 v[86:89], v[132:133], off offset:128
	v_and_b32_e32 v63, 31, v58
	v_lshrrev_b32_e32 v58, 1, v58
	v_and_or_b32 v64, v58, s47, v63
	v_and_b32_e32 v65, 16, v58
	v_and_or_b32 v58, v58, 32, v63
	v_mad_u64_u32 v[134:135], s[6:7], v59, s76, v[0:1]
	v_mad_u64_u32 v[136:137], s[6:7], v60, s76, v[0:1]
	v_mad_u64_u32 v[138:139], s[6:7], v61, s76, v[0:1]
	v_mad_u64_u32 v[140:141], s[6:7], v62, s76, v[0:1]
	v_mul_u32_u24_e32 v58, 0x90, v58
	v_mul_lo_u32 v0, v64, s76
	s_mov_b32 s5, 3
	s_add_i32 s6, s4, -1
	v_add_u32_e32 v0, v65, v0
	v_add_u32_e32 v135, v58, v65
	v_readlane_b32 s18, v252, 59
	v_readlane_b32 s19, v252, 60
	v_readlane_b32 s20, v252, 61
	v_readlane_b32 s21, v252, 62
	v_readlane_b32 s22, v252, 63
	v_readlane_b32 s23, v253, 0
	v_readlane_b32 s24, v253, 1
	v_readlane_b32 s25, v253, 2
	v_readlane_b32 s26, v253, 3
	v_readlane_b32 s27, v253, 4
	v_readlane_b32 s30, v253, 7
	v_readlane_b32 s31, v253, 8
	s_waitcnt vmcnt(11)
	ds_write_b128 v134, v[34:37]
	s_waitcnt vmcnt(10)
	ds_write_b128 v136, v[38:41]
	s_waitcnt vmcnt(9)
	ds_write_b128 v138, v[42:45]
	s_waitcnt vmcnt(8)
	ds_write_b128 v140, v[46:49]
	s_waitcnt vmcnt(7)
	ds_write_b128 v134, v[50:53] offset:18432
	s_waitcnt vmcnt(6)
	ds_write_b128 v136, v[54:57] offset:18432
	v_mov_b32_e32 v34, 0
	v_mov_b32_e32 v35, v34
	v_mov_b32_e32 v36, v34
	v_mov_b32_e32 v37, v34
	v_mov_b32_e32 v38, v34
	v_mov_b32_e32 v39, v34
	v_mov_b32_e32 v40, v34
	v_mov_b32_e32 v41, v34
	v_mov_b32_e32 v42, v34
	v_mov_b32_e32 v43, v34
	v_mov_b32_e32 v44, v34
	v_mov_b32_e32 v45, v34
	v_mov_b32_e32 v46, v34
	v_mov_b32_e32 v47, v34
	v_mov_b32_e32 v48, v34
	v_mov_b32_e32 v49, v34
	v_mov_b32_e32 v50, v34
	v_mov_b32_e32 v51, v34
	v_mov_b32_e32 v52, v34
	v_mov_b32_e32 v53, v34
	v_mov_b32_e32 v54, v34
	v_mov_b32_e32 v55, v34
	v_mov_b32_e32 v56, v34
	v_mov_b32_e32 v57, v34
	v_mov_b32_e32 v58, v34
	v_mov_b32_e32 v59, v34
	v_mov_b32_e32 v60, v34
	v_mov_b32_e32 v61, v34
	v_mov_b32_e32 v62, v34
	v_mov_b32_e32 v63, v34
	v_mov_b32_e32 v64, v34
	v_mov_b32_e32 v65, v34
	s_waitcnt lgkmcnt(0)
	s_barrier
.LBB0_21:
	s_add_i32 s7, s5, -1
	s_cmp_lt_u32 s7, s4
	s_cbranch_scc0 .Lpeel_tail_21
	ds_read_b128 v[176:179], v0
	ds_read_b128 v[180:183], v135 offset:18432
	ds_read_b128 v[184:187], v0 offset:4608
	s_add_i32 s7, s5, -1
	s_min_u32 s14, s7, s6
	s_lshl_b64 s[8:9], s[14:15], 7
	v_lshl_add_u64 v[144:145], v[122:123], 0, s[8:9]
	v_lshl_add_u64 v[148:149], v[124:125], 0, s[8:9]
	v_lshl_add_u64 v[152:153], v[126:127], 0, s[8:9]
	v_lshl_add_u64 v[156:157], v[128:129], 0, s[8:9]
	v_lshl_add_u64 v[160:161], v[130:131], 0, s[8:9]
	v_lshl_add_u64 v[164:165], v[132:133], 0, s[8:9]
	s_setprio 1
	ds_read_b128 v[188:191], v0 offset:32
	ds_read_b128 v[192:195], v135 offset:18464
	ds_read_b128 v[196:199], v0 offset:4640
	s_waitcnt lgkmcnt(3)
	v_mfma_f32_32x32x16_bf16 v[50:65], v[176:179], v[180:183], v[50:65]
	global_load_dwordx4 v[144:147], v[144:145], off
	s_nop 0
	global_load_dwordx4 v[148:151], v[148:149], off
	v_mfma_f32_32x32x16_bf16 v[34:49], v[184:187], v[180:183], v[34:49]
	global_load_dwordx4 v[152:155], v[152:153], off
	ds_read_b128 v[176:179], v0 offset:64
	ds_read_b128 v[180:183], v135 offset:18496
	ds_read_b128 v[184:187], v0 offset:4672
	s_waitcnt lgkmcnt(3)
	v_mfma_f32_32x32x16_bf16 v[50:65], v[188:191], v[192:195], v[50:65]
	global_load_dwordx4 v[156:159], v[156:157], off
	s_nop 0
	global_load_dwordx4 v[160:163], v[160:161], off
	v_mfma_f32_32x32x16_bf16 v[34:49], v[196:199], v[192:195], v[34:49]
	global_load_dwordx4 v[164:167], v[164:165], off
	ds_read_b128 v[188:191], v0 offset:96
	ds_read_b128 v[192:195], v135 offset:18528
	ds_read_b128 v[196:199], v0 offset:4704
	s_waitcnt lgkmcnt(3)
	v_mfma_f32_32x32x16_bf16 v[50:65], v[176:179], v[180:183], v[50:65]
	s_waitcnt vmcnt(6)
	ds_write_b128 v134, v[66:69] offset:27648
	ds_write_b128 v136, v[70:73] offset:27648
	v_mfma_f32_32x32x16_bf16 v[34:49], v[184:187], v[180:183], v[34:49]
	ds_write_b128 v138, v[74:77] offset:27648
	s_waitcnt lgkmcnt(3)
	v_mfma_f32_32x32x16_bf16 v[50:65], v[188:191], v[192:195], v[50:65]
	ds_write_b128 v140, v[78:81] offset:27648
	ds_write_b128 v134, v[82:85] offset:46080
	v_mfma_f32_32x32x16_bf16 v[34:49], v[196:199], v[192:195], v[34:49]
	ds_write_b128 v136, v[86:89] offset:46080
	s_setprio 0
	s_min_u32 s14, s5, s6
	s_lshl_b64 s[8:9], s[14:15], 7
	v_lshl_add_u64 v[66:67], v[122:123], 0, s[8:9]
	v_lshl_add_u64 v[70:71], v[124:125], 0, s[8:9]
	v_lshl_add_u64 v[74:75], v[126:127], 0, s[8:9]
	v_lshl_add_u64 v[78:79], v[128:129], 0, s[8:9]
	v_lshl_add_u64 v[82:83], v[130:131], 0, s[8:9]
	v_lshl_add_u64 v[86:87], v[132:133], 0, s[8:9]
	s_waitcnt lgkmcnt(0)
	s_barrier
	ds_read_b128 v[176:179], v0 offset:27648
	ds_read_b128 v[180:183], v135 offset:46080
	ds_read_b128 v[184:187], v0 offset:32256
	s_setprio 1
	ds_read_b128 v[188:191], v0 offset:27680
	ds_read_b128 v[192:195], v135 offset:46112
	ds_read_b128 v[196:199], v0 offset:32288
	s_waitcnt lgkmcnt(3)
	v_mfma_f32_32x32x16_bf16 v[50:65], v[176:179], v[180:183], v[50:65]
	global_load_dwordx4 v[66:69], v[66:67], off
	s_nop 0
	global_load_dwordx4 v[70:73], v[70:71], off
	v_mfma_f32_32x32x16_bf16 v[34:49], v[184:187], v[180:183], v[34:49]
	global_load_dwordx4 v[74:77], v[74:75], off
	ds_read_b128 v[176:179], v0 offset:27712
	ds_read_b128 v[180:183], v135 offset:46144
	ds_read_b128 v[184:187], v0 offset:32320
	s_waitcnt lgkmcnt(3)
	v_mfma_f32_32x32x16_bf16 v[50:65], v[188:191], v[192:195], v[50:65]
	global_load_dwordx4 v[78:81], v[78:79], off
	s_nop 0
	global_load_dwordx4 v[82:85], v[82:83], off
	v_mfma_f32_32x32x16_bf16 v[34:49], v[196:199], v[192:195], v[34:49]
	global_load_dwordx4 v[86:89], v[86:87], off
	ds_read_b128 v[188:191], v0 offset:27744
	ds_read_b128 v[192:195], v135 offset:46176
	ds_read_b128 v[196:199], v0 offset:32352
	s_waitcnt lgkmcnt(3)
	v_mfma_f32_32x32x16_bf16 v[50:65], v[176:179], v[180:183], v[50:65]
	s_waitcnt vmcnt(6)
	ds_write_b128 v134, v[144:147]
	ds_write_b128 v136, v[148:151]
	v_mfma_f32_32x32x16_bf16 v[34:49], v[184:187], v[180:183], v[34:49]
	ds_write_b128 v138, v[152:155]
	s_waitcnt lgkmcnt(3)
	v_mfma_f32_32x32x16_bf16 v[50:65], v[188:191], v[192:195], v[50:65]
	ds_write_b128 v140, v[156:159]
	ds_write_b128 v134, v[160:163] offset:18432
	v_mfma_f32_32x32x16_bf16 v[34:49], v[196:199], v[192:195], v[34:49]
	ds_write_b128 v136, v[164:167] offset:18432
	s_setprio 0
	s_add_i32 s5, s5, 2
	s_cmp_lt_u32 s7, s4
	s_waitcnt lgkmcnt(0)
	s_barrier
	s_branch .LBB0_21
; DI float sigmoidf(float x) { return __builtin_amdgcn_rcpf(1.f + __expf(-x)); }
; #define G_STORE(ST, S, unused) do { char* d_ = smem + (ST) * STAGE; \
;     *(uint4*)(d_ + alo[0]) = S##a0; *(uint4*)(d_ + alo[1]) = S##a1; *(uint4*)(d_ + alo[2]) = S##a2; *(uint4*)(d_ + alo[3]) = S##a3; \
;     *(uint4*)(d_ + blo[0]) = S##b0; *(uint4*)(d_ + blo[1]) = S##b1; \
;     if (NBCH == 4) { *(uint4*)(d_ + blo[NBCH - 2]) = S##b2; *(uint4*)(d_ + blo[NBCH - 1]) = S##b3; } } while (0)
; template <int NJ, class RowA>
; DI void gemm_main(f32x16 (&acc)[2][NJ], const bf16_t* __restrict__ A, RowA rowA, size_t kstrideA, int m0, int Mmax,
;                   const bf16_t* __restrict__ Bt, size_t ldb, int n0, int nk, char* smem) {
;     ...
;   __syncthreads();
;   G_LOAD(x0, 0, 0);
;   G_LOAD(x1, 0, 1);
;   G_STORE(0, x0, 0);
;   __syncthreads();
; #pragma unroll 1
;   for (int kt = 0; kt < nk; kt += 2) {
;     G_LOAD(x0, 0, (kt + 2 < nk ? kt + 2 : nk - 1));
;     G_COMPUTE(0);
;     G_STORE(1, x1, 0);
;     __syncthreads();
;     G_LOAD(x1, 0, (kt + 3 < nk ? kt + 3 : nk - 1));
;     G_COMPUTE(1);
;     G_STORE(0, x0, 0);
;     __syncthreads();
;   }
; DI void merge_tile(const Params& p, int mt, int nt, char* smem) {
;     ...
;     for (int i = 0; i < 2; ++i)
; #pragma unroll
;       for (int e = 0; e < 16; ++e) mac[i][0][e] += sigmoidf(ag[i][0][e]) * ap[i][0][e];
.Lpeel_tail_21:
	ds_read_b128 v[176:179], v0
	ds_read_b128 v[180:183], v135 offset:18432
	ds_read_b128 v[184:187], v0 offset:4608
	s_add_i32 s7, s5, -1
	s_min_u32 s14, s7, s6
	s_lshl_b64 s[8:9], s[14:15], 7
	v_lshl_add_u64 v[144:145], v[122:123], 0, s[8:9]
	v_lshl_add_u64 v[148:149], v[124:125], 0, s[8:9]
	v_lshl_add_u64 v[152:153], v[126:127], 0, s[8:9]
	v_lshl_add_u64 v[156:157], v[128:129], 0, s[8:9]
	v_lshl_add_u64 v[160:161], v[130:131], 0, s[8:9]
	v_lshl_add_u64 v[164:165], v[132:133], 0, s[8:9]
	s_setprio 1
	ds_read_b128 v[188:191], v0 offset:32
	ds_read_b128 v[192:195], v135 offset:18464
	ds_read_b128 v[196:199], v0 offset:4640
	s_waitcnt lgkmcnt(3)
	v_mfma_f32_32x32x16_bf16 v[50:65], v[176:179], v[180:183], v[50:65]
	v_mfma_f32_32x32x16_bf16 v[34:49], v[184:187], v[180:183], v[34:49]
	ds_read_b128 v[176:179], v0 offset:64
	ds_read_b128 v[180:183], v135 offset:18496
	ds_read_b128 v[184:187], v0 offset:4672
	s_waitcnt lgkmcnt(3)
	v_mfma_f32_32x32x16_bf16 v[50:65], v[188:191], v[192:195], v[50:65]
	v_mfma_f32_32x32x16_bf16 v[34:49], v[196:199], v[192:195], v[34:49]
	ds_read_b128 v[188:191], v0 offset:96
	ds_read_b128 v[192:195], v135 offset:18528
	ds_read_b128 v[196:199], v0 offset:4704
	s_waitcnt lgkmcnt(3)
	v_mfma_f32_32x32x16_bf16 v[50:65], v[176:179], v[180:183], v[50:65]
	s_waitcnt vmcnt(0)
	ds_write_b128 v134, v[66:69] offset:27648
	ds_write_b128 v136, v[70:73] offset:27648
	v_mfma_f32_32x32x16_bf16 v[34:49], v[184:187], v[180:183], v[34:49]
	ds_write_b128 v138, v[74:77] offset:27648
	s_waitcnt lgkmcnt(3)
	v_mfma_f32_32x32x16_bf16 v[50:65], v[188:191], v[192:195], v[50:65]
	ds_write_b128 v140, v[78:81] offset:27648
	ds_write_b128 v134, v[82:85] offset:46080
	v_mfma_f32_32x32x16_bf16 v[34:49], v[196:199], v[192:195], v[34:49]
	ds_write_b128 v136, v[86:89] offset:46080
	s_setprio 0
	s_min_u32 s14, s5, s6
	s_lshl_b64 s[8:9], s[14:15], 7
	v_lshl_add_u64 v[66:67], v[122:123], 0, s[8:9]
	v_lshl_add_u64 v[70:71], v[124:125], 0, s[8:9]
	v_lshl_add_u64 v[74:75], v[126:127], 0, s[8:9]
	v_lshl_add_u64 v[78:79], v[128:129], 0, s[8:9]
	v_lshl_add_u64 v[82:83], v[130:131], 0, s[8:9]
	v_lshl_add_u64 v[86:87], v[132:133], 0, s[8:9]
	s_waitcnt lgkmcnt(0)
	s_barrier
	ds_read_b128 v[176:179], v0 offset:27648
	ds_read_b128 v[180:183], v135 offset:46080
	ds_read_b128 v[184:187], v0 offset:32256
	s_setprio 1
	ds_read_b128 v[188:191], v0 offset:27680
	ds_read_b128 v[192:195], v135 offset:46112
	ds_read_b128 v[196:199], v0 offset:32288
	s_waitcnt lgkmcnt(3)
	v_mfma_f32_32x32x16_bf16 v[50:65], v[176:179], v[180:183], v[50:65]
	v_mfma_f32_32x32x16_bf16 v[34:49], v[184:187], v[180:183], v[34:49]
	ds_read_b128 v[176:179], v0 offset:27712
	ds_read_b128 v[180:183], v135 offset:46144
	ds_read_b128 v[184:187], v0 offset:32320
	s_waitcnt lgkmcnt(3)
	v_mfma_f32_32x32x16_bf16 v[50:65], v[188:191], v[192:195], v[50:65]
	v_mfma_f32_32x32x16_bf16 v[34:49], v[196:199], v[192:195], v[34:49]
	ds_read_b128 v[188:191], v0 offset:27744
	ds_read_b128 v[192:195], v135 offset:46176
	ds_read_b128 v[196:199], v0 offset:32352
	s_waitcnt lgkmcnt(3)
	v_mfma_f32_32x32x16_bf16 v[50:65], v[176:179], v[180:183], v[50:65]
	v_mfma_f32_32x32x16_bf16 v[34:49], v[184:187], v[180:183], v[34:49]
	s_waitcnt lgkmcnt(0)
	v_mfma_f32_32x32x16_bf16 v[50:65], v[188:191], v[192:195], v[50:65]
	v_mfma_f32_32x32x16_bf16 v[34:49], v[196:199], v[192:195], v[34:49]
	s_setprio 0
	s_add_i32 s5, s5, 2
	s_cmp_lt_u32 s7, s4
	s_waitcnt lgkmcnt(0)
	s_barrier
	v_mul_f32_e32 v0, 0xbfb8aa3b, v18
	v_exp_f32_e32 v0, v0
	v_mul_f32_e32 v18, 0xbfb8aa3b, v19
	v_exp_f32_e32 v18, v18
	s_add_i32 s3, s3, 1
	v_add_f32_e32 v0, 1.0, v0
	s_cmp_lg_u32 s3, 3
	v_add_f32_e32 v19, 1.0, v18
	v_rcp_f32_e32 v18, v0
	v_mul_f32_e32 v0, 0xbfb8aa3b, v20
	v_exp_f32_e32 v0, v0
	v_mul_f32_e32 v20, 0xbfb8aa3b, v21
	v_rcp_f32_e32 v19, v19
	v_exp_f32_e32 v20, v20
	v_add_f32_e32 v0, 1.0, v0
	v_pk_fma_f32 v[120:121], v[18:19], v[50:51], v[120:121]
	v_rcp_f32_e32 v18, v0
	v_add_f32_e32 v0, 1.0, v20
	v_rcp_f32_e32 v19, v0
	v_mul_f32_e32 v0, 0xbfb8aa3b, v22
	v_exp_f32_e32 v0, v0
	v_mul_f32_e32 v20, 0xbfb8aa3b, v23
	v_exp_f32_e32 v20, v20
	v_pk_fma_f32 v[118:119], v[18:19], v[52:53], v[118:119]
	v_add_f32_e32 v0, 1.0, v0
	v_rcp_f32_e32 v18, v0
	v_add_f32_e32 v0, 1.0, v20
	v_rcp_f32_e32 v19, v0
	v_mul_f32_e32 v0, 0xbfb8aa3b, v24
	v_exp_f32_e32 v0, v0
	v_mul_f32_e32 v20, 0xbfb8aa3b, v25
	v_exp_f32_e32 v20, v20
	v_pk_fma_f32 v[116:117], v[18:19], v[54:55], v[116:117]
	v_add_f32_e32 v0, 1.0, v0
	v_rcp_f32_e32 v18, v0
	v_add_f32_e32 v0, 1.0, v20
	v_rcp_f32_e32 v19, v0
	v_mul_f32_e32 v0, 0xbfb8aa3b, v26
	v_exp_f32_e32 v0, v0
	v_mul_f32_e32 v20, 0xbfb8aa3b, v27
	v_exp_f32_e32 v20, v20
	v_pk_fma_f32 v[114:115], v[18:19], v[56:57], v[114:115]
	v_add_f32_e32 v0, 1.0, v0
	v_rcp_f32_e32 v18, v0
	v_add_f32_e32 v0, 1.0, v20
	v_rcp_f32_e32 v19, v0
	v_mul_f32_e32 v0, 0xbfb8aa3b, v28
	v_exp_f32_e32 v0, v0
	v_mul_f32_e32 v20, 0xbfb8aa3b, v29
	v_exp_f32_e32 v20, v20
	v_pk_fma_f32 v[112:113], v[18:19], v[58:59], v[112:113]
	v_add_f32_e32 v0, 1.0, v0
	v_rcp_f32_e32 v18, v0
	v_add_f32_e32 v0, 1.0, v20
	v_rcp_f32_e32 v19, v0
	v_mul_f32_e32 v0, 0xbfb8aa3b, v30
	v_exp_f32_e32 v0, v0
	v_mul_f32_e32 v20, 0xbfb8aa3b, v31
	v_exp_f32_e32 v20, v20
	v_pk_fma_f32 v[110:111], v[18:19], v[60:61], v[110:111]
	v_add_f32_e32 v0, 1.0, v0
	v_rcp_f32_e32 v18, v0
	v_add_f32_e32 v0, 1.0, v20
	v_rcp_f32_e32 v19, v0
	v_mul_f32_e32 v0, 0xbfb8aa3b, v32
	v_exp_f32_e32 v0, v0
	v_mul_f32_e32 v20, 0xbfb8aa3b, v33
	v_exp_f32_e32 v20, v20
	v_pk_fma_f32 v[108:109], v[18:19], v[62:63], v[108:109]
	v_add_f32_e32 v0, 1.0, v0
	v_rcp_f32_e32 v18, v0
	v_add_f32_e32 v0, 1.0, v20
	v_rcp_f32_e32 v19, v0
; #define TIDX (tid_launder())
; DI int crow(int reg, int hh) { return (reg & 3) + 8 * (reg >> 2) + 4 * hh; }
; DI float sigmoidf(float x) { return __builtin_amdgcn_rcpf(1.f + __expf(-x)); }
; template <int NJ>
; DI void acc_to_ct(const f32x16 (&acc)[2][NJ], float* Ct) {
;   const int lane = TIDX & 63, wid = TIDX >> 6, wm = wid >> 1, wn = wid & 1;
;   const int r = lane & 31, hh = lane >> 5;
; #pragma unroll
;   for (int i = 0; i < 2; ++i)
; #pragma unroll
;     for (int j = 0; j < NJ; ++j)
; #pragma unroll
;       for (int e = 0; e < 16; ++e) Ct[(wm * 64 + i * 32 + crow(e, hh)) * 132 + wn * 32 * NJ + j * 32 + r] = acc[i][j][e];
;   __syncthreads();
; DI void merge_tile(const Params& p, int mt, int nt, char* smem) {
;     ...
;     for (int i = 0; i < 2; ++i)
; #pragma unroll
;       for (int e = 0; e < 16; ++e) mac[i][0][e] += sigmoidf(ag[i][0][e]) * ap[i][0][e];
;   }
;   float* Ct = (float*)smem;
;   acc_to_ct<1>(mac, Ct);
	v_mul_f32_e32 v0, 0xbfb8aa3b, v2
	v_exp_f32_e32 v0, v0
	v_mul_f32_e32 v2, 0xbfb8aa3b, v3
	v_exp_f32_e32 v3, v2
	v_pk_fma_f32 v[106:107], v[18:19], v[64:65], v[106:107]
	v_add_f32_e32 v0, 1.0, v0
	v_rcp_f32_e32 v2, v0
	v_add_f32_e32 v0, 1.0, v3
	v_rcp_f32_e32 v3, v0
	v_mul_f32_e32 v0, 0xbfb8aa3b, v4
	v_exp_f32_e32 v0, v0
	v_mul_f32_e32 v4, 0xbfb8aa3b, v5
	v_exp_f32_e32 v4, v4
	v_pk_fma_f32 v[104:105], v[2:3], v[34:35], v[104:105]
	v_add_f32_e32 v0, 1.0, v0
	v_rcp_f32_e32 v2, v0
	v_add_f32_e32 v0, 1.0, v4
	v_rcp_f32_e32 v3, v0
	v_mul_f32_e32 v0, 0xbfb8aa3b, v6
	v_exp_f32_e32 v0, v0
	v_mul_f32_e32 v4, 0xbfb8aa3b, v7
	v_exp_f32_e32 v4, v4
	v_pk_fma_f32 v[102:103], v[2:3], v[36:37], v[102:103]
	v_add_f32_e32 v0, 1.0, v0
	v_rcp_f32_e32 v2, v0
	v_add_f32_e32 v0, 1.0, v4
	v_rcp_f32_e32 v3, v0
	v_mul_f32_e32 v0, 0xbfb8aa3b, v8
	v_exp_f32_e32 v0, v0
	v_mul_f32_e32 v4, 0xbfb8aa3b, v9
	v_exp_f32_e32 v4, v4
	v_pk_fma_f32 v[100:101], v[2:3], v[38:39], v[100:101]
	v_add_f32_e32 v0, 1.0, v0
	v_rcp_f32_e32 v2, v0
	v_add_f32_e32 v0, 1.0, v4
	v_rcp_f32_e32 v3, v0
	v_mul_f32_e32 v0, 0xbfb8aa3b, v10
	v_exp_f32_e32 v0, v0
	v_mul_f32_e32 v4, 0xbfb8aa3b, v11
	v_exp_f32_e32 v4, v4
	v_pk_fma_f32 v[98:99], v[2:3], v[40:41], v[98:99]
	v_add_f32_e32 v0, 1.0, v0
	v_rcp_f32_e32 v2, v0
	v_add_f32_e32 v0, 1.0, v4
	v_rcp_f32_e32 v3, v0
	v_mul_f32_e32 v0, 0xbfb8aa3b, v12
	v_exp_f32_e32 v0, v0
	v_mul_f32_e32 v4, 0xbfb8aa3b, v13
	v_exp_f32_e32 v4, v4
	v_pk_fma_f32 v[96:97], v[2:3], v[42:43], v[96:97]
	v_add_f32_e32 v0, 1.0, v0
	v_rcp_f32_e32 v2, v0
	v_add_f32_e32 v0, 1.0, v4
	v_rcp_f32_e32 v3, v0
	v_mul_f32_e32 v0, 0xbfb8aa3b, v14
	v_exp_f32_e32 v0, v0
	v_mul_f32_e32 v4, 0xbfb8aa3b, v15
	v_exp_f32_e32 v4, v4
	v_pk_fma_f32 v[94:95], v[2:3], v[44:45], v[94:95]
	v_add_f32_e32 v0, 1.0, v0
	v_mul_f32_e32 v3, 0xbfb8aa3b, v16
	v_rcp_f32_e32 v2, v0
	v_add_f32_e32 v0, 1.0, v4
	v_exp_f32_e32 v4, v3
	v_mul_f32_e32 v3, 0xbfb8aa3b, v17
	v_exp_f32_e32 v5, v3
	v_rcp_f32_e32 v3, v0
	v_add_f32_e32 v0, 1.0, v4
	v_rcp_f32_e32 v4, v0
	v_add_f32_e32 v0, 1.0, v5
	v_rcp_f32_e32 v5, v0
	v_pk_fma_f32 v[92:93], v[2:3], v[46:47], v[92:93]
	v_pk_fma_f32 v[90:91], v[4:5], v[48:49], v[90:91]
	s_cbranch_scc1 .LBB0_18
	v_mov_b32_e32 v0, v230
	v_mov_b32_e32 v2, v230
	v_and_b32_e32 v3, 31, v0
	v_lshrrev_b32_e32 v0, 3, v0
	v_and_b32_e32 v0, 4, v0
	v_lshrrev_b32_e32 v4, 1, v2
	v_and_or_b32 v4, v4, s47, v0
	v_lshlrev_b32_e32 v0, 1, v2
	v_and_b32_e32 v0, 0x80, v0
	v_lshl_or_b32 v0, v3, 2, v0
	v_mad_u64_u32 v[2:3], s[4:5], v4, s79, v[0:1]
	v_add_u32_e32 v0, 0x400, v2
	ds_write2_b32 v0, v118, v119 offset0:8 offset1:140
	v_add_u32_e32 v0, 0x1000, v2
	ds_write2_b32 v0, v116, v117 offset0:32 offset1:164
	v_add_u32_e32 v0, 0x1400, v2
	ds_write2_b32 v0, v114, v115 offset0:40 offset1:172
	v_add_u32_e32 v0, 0x2000, v2
	ds_write2_b32 v0, v112, v113 offset0:64 offset1:196
	v_add_u32_e32 v0, 0x2400, v2
	ds_write2_b32 v0, v110, v111 offset0:72 offset1:204
	v_add_u32_e32 v0, 0x3000, v2
	ds_write2_b32 v0, v108, v109 offset0:96 offset1:228
	v_add_u32_e32 v0, 0x3400, v2
	ds_write2_b32 v0, v106, v107 offset0:104 offset1:236
	v_add_u32_e32 v0, 0x4200, v2
	ds_write2_b32 v0, v104, v105 offset1:132
	v_add_u32_e32 v0, 0x4600, v2
	ds_write2_b32 v0, v102, v103 offset0:8 offset1:140
	v_add_u32_e32 v0, 0x5200, v2
	ds_write2_b32 v0, v100, v101 offset0:32 offset1:164
	v_add_u32_e32 v0, 0x5600, v2
	ds_write2_b32 v0, v98, v99 offset0:40 offset1:172
	v_add_u32_e32 v0, 0x6200, v2
	ds_write2_b32 v0, v96, v97 offset0:64 offset1:196
	v_add_u32_e32 v0, 0x6600, v2
	ds_write2_b32 v0, v94, v95 offset0:72 offset1:204
	v_add_u32_e32 v0, 0x7200, v2
	ds_write2_b32 v0, v92, v93 offset0:96 offset1:228
	v_add_u32_e32 v0, 0x7600, v2
	ds_write2_b32 v0, v90, v91 offset0:104 offset1:236
	v_mov_b32_e32 v0, v230
	ds_write2_b32 v2, v120, v121 offset1:132
	s_waitcnt lgkmcnt(0)
	s_barrier
; #define TIDX (tid_launder())
; DI unsigned pack2(float a, float b) { hwf2 v = {a, b}; hwbf2 r = __builtin_convertvector(v, hwbf2); return __builtin_bit_cast(unsigned, r); }
; DI float siluf(float x) { return x * __builtin_amdgcn_rcpf(1.f + __expf(-x)); }
; DI void epi_store64(const float* Ct, int cb, const float* rn, int grp, const float* gain, bool silu, const float* bias,
;                     bf16_t* dst, size_t ldd, int dcol0, int m0, int Mmax) {
;   const int tid = TIDX, c = (tid & 15) * 4;
;   float4 gv = make_float4(1.f, 1.f, 1.f, 1.f), bv = make_float4(0.f, 0.f, 0.f, 0.f);
;   if (rn) gv = *(const float4*)(gain + c);
;   if (bias) bv = *(const float4*)(bias + c);
; #pragma unroll
;   for (int q = 0; q < 8; ++q) {
;     const int row = (tid >> 4) + 16 * q;
;     float4 v = *(const float4*)(Ct + row * 132 + cb + c);
;     v.x += bv.x; v.y += bv.y; v.z += bv.z; v.w += bv.w;
;     if (rn) { const float sc = rn[row * 2 + grp]; v.x *= sc * gv.x; v.y *= sc * gv.y; v.z *= sc * gv.z; v.w *= sc * gv.w; }
;     if (silu) { v.x = siluf(v.x); v.y = siluf(v.y); v.z = siluf(v.z); v.w = siluf(v.w); }
;     uint2 o; o.x = pack2(v.x, v.y); o.y = pack2(v.z, v.w);
;     *(uint2*)(dst + (size_t)(m0 + row) * ldd + dcol0 + c) = o;
;   }
; __global__ void __launch_bounds__(256, 2) mega(Params p, int ph_lo, int ph_hi) {
;     ...
;         for (int idx = blockIdx.x >> 3; idx < 512; idx += gridDim.x >> 3) { const int t = (blockIdx.x & 7) * 512 + idx; merge_tile(p, t >> 4, t & 15, smem); }
	s_lshl_b32 s2, s2, 1
	v_lshlrev_b32_e32 v2, 2, v0
	v_ashrrev_i32_e32 v12, 4, v0
	v_and_b32_e32 v6, 60, v2
	v_mul_lo_u32 v0, v12, s79
	v_lshl_add_u32 v14, v6, 2, v0
	ds_read_b128 v[2:5], v14
	v_readlane_b32 s4, v250, 50
	v_lshlrev_b32_e32 v0, 1, v6
	ds_read_b128 v[6:9], v14 offset:8448
	v_readlane_b32 s5, v250, 51
	s_add_u32 s2, s4, s2
	v_add_u32_e32 v12, s1, v12
	s_addc_u32 s3, s5, 0
	s_waitcnt lgkmcnt(1)
	v_pk_add_f32 v[2:3], v[2:3], 0 op_sel_hi:[1,0]
	v_pk_add_f32 v[4:5], v[4:5], 0 op_sel_hi:[1,0]
	v_ashrrev_i32_e32 v13, 31, v12
	v_lshl_add_u64 v[10:11], s[2:3], 0, v[0:1]
	v_cvt_pk_bf16_f32 v2, v2, v3
	v_cvt_pk_bf16_f32 v3, v4, v5
	v_lshlrev_b64 v[4:5], 11, v[12:13]
	v_lshl_add_u64 v[4:5], v[10:11], 0, v[4:5]
	global_store_dwordx2 v[4:5], v[2:3], off
	s_waitcnt lgkmcnt(0)
	v_pk_add_f32 v[2:3], v[6:7], 0 op_sel_hi:[1,0]
	v_pk_add_f32 v[4:5], v[8:9], 0 op_sel_hi:[1,0]
	v_cvt_pk_bf16_f32 v6, v2, v3
	v_cvt_pk_bf16_f32 v7, v4, v5
	ds_read_b128 v[2:5], v14 offset:16896
	v_add_u32_e32 v8, 16, v12
	v_ashrrev_i32_e32 v9, 31, v8
	v_lshlrev_b64 v[8:9], 11, v[8:9]
	v_lshl_add_u64 v[8:9], v[10:11], 0, v[8:9]
	global_store_dwordx2 v[8:9], v[6:7], off
	ds_read_b128 v[6:9], v14 offset:25344
	s_waitcnt lgkmcnt(1)
	v_pk_add_f32 v[2:3], v[2:3], 0 op_sel_hi:[1,0]
	v_pk_add_f32 v[4:5], v[4:5], 0 op_sel_hi:[1,0]
	v_cvt_pk_bf16_f32 v2, v2, v3
	v_cvt_pk_bf16_f32 v3, v4, v5
	v_add_u32_e32 v4, 32, v12
	v_ashrrev_i32_e32 v5, 31, v4
	v_lshlrev_b64 v[4:5], 11, v[4:5]
	v_lshl_add_u64 v[4:5], v[10:11], 0, v[4:5]
	global_store_dwordx2 v[4:5], v[2:3], off
	s_waitcnt lgkmcnt(0)
	v_pk_add_f32 v[2:3], v[6:7], 0 op_sel_hi:[1,0]
	v_pk_add_f32 v[4:5], v[8:9], 0 op_sel_hi:[1,0]
	v_cvt_pk_bf16_f32 v6, v2, v3
	v_cvt_pk_bf16_f32 v7, v4, v5
	ds_read_b128 v[2:5], v14 offset:33792
	v_add_u32_e32 v8, 48, v12
	v_ashrrev_i32_e32 v9, 31, v8
	v_lshlrev_b64 v[8:9], 11, v[8:9]
	v_lshl_add_u64 v[8:9], v[10:11], 0, v[8:9]
	global_store_dwordx2 v[8:9], v[6:7], off
	ds_read_b128 v[6:9], v14 offset:42240
	s_waitcnt lgkmcnt(1)
	v_pk_add_f32 v[2:3], v[2:3], 0 op_sel_hi:[1,0]
	v_pk_add_f32 v[4:5], v[4:5], 0 op_sel_hi:[1,0]
	v_cvt_pk_bf16_f32 v2, v2, v3
	v_cvt_pk_bf16_f32 v3, v4, v5
	v_add_u32_e32 v4, 64, v12
	v_ashrrev_i32_e32 v5, 31, v4
	v_lshlrev_b64 v[4:5], 11, v[4:5]
	v_lshl_add_u64 v[4:5], v[10:11], 0, v[4:5]
	global_store_dwordx2 v[4:5], v[2:3], off
	s_waitcnt lgkmcnt(0)
	v_pk_add_f32 v[2:3], v[6:7], 0 op_sel_hi:[1,0]
	v_pk_add_f32 v[4:5], v[8:9], 0 op_sel_hi:[1,0]
	v_cvt_pk_bf16_f32 v6, v2, v3
	v_cvt_pk_bf16_f32 v7, v4, v5
	ds_read_b128 v[2:5], v14 offset:50688
	v_add_u32_e32 v8, 0x50, v12
	v_ashrrev_i32_e32 v9, 31, v8
	v_lshlrev_b64 v[8:9], 11, v[8:9]
	v_lshl_add_u64 v[8:9], v[10:11], 0, v[8:9]
	global_store_dwordx2 v[8:9], v[6:7], off
	ds_read_b128 v[6:9], v14 offset:59136
	s_waitcnt lgkmcnt(1)
	v_pk_add_f32 v[2:3], v[2:3], 0 op_sel_hi:[1,0]
	v_pk_add_f32 v[4:5], v[4:5], 0 op_sel_hi:[1,0]
	v_cvt_pk_bf16_f32 v2, v2, v3
	v_cvt_pk_bf16_f32 v3, v4, v5
	v_add_u32_e32 v4, 0x60, v12
	v_ashrrev_i32_e32 v5, 31, v4
	v_lshlrev_b64 v[4:5], 11, v[4:5]
	v_lshl_add_u64 v[4:5], v[10:11], 0, v[4:5]
	global_store_dwordx2 v[4:5], v[2:3], off
	s_waitcnt lgkmcnt(0)
	v_pk_add_f32 v[2:3], v[6:7], 0 op_sel_hi:[1,0]
	v_pk_add_f32 v[4:5], v[8:9], 0 op_sel_hi:[1,0]
	v_cvt_pk_bf16_f32 v2, v2, v3
	v_cvt_pk_bf16_f32 v3, v4, v5
	v_add_u32_e32 v4, 0x70, v12
	v_ashrrev_i32_e32 v5, 31, v4
	v_readlane_b32 s1, v250, 60
	v_lshlrev_b64 v[4:5], 11, v[4:5]
	s_add_i32 s0, s0, s1
	v_lshl_add_u64 v[4:5], v[10:11], 0, v[4:5]
	s_cmpk_gt_u32 s0, 0x1ff
	v_readlane_b32 s6, v250, 52
	v_readlane_b32 s7, v250, 53
	global_store_dwordx2 v[4:5], v[2:3], off
	s_barrier
	s_cbranch_scc0 .LBB0_17

; #define G_STORE(ST, S, unused) do { char* d_ = smem + (ST) * STAGE; \
;     *(uint4*)(d_ + alo[0]) = S##a0; *(uint4*)(d_ + alo[1]) = S##a1; *(uint4*)(d_ + alo[2]) = S##a2; *(uint4*)(d_ + alo[3]) = S##a3; \
;     *(uint4*)(d_ + blo[0]) = S##b0; *(uint4*)(d_ + blo[1]) = S##b1; \
;     if (NBCH == 4) { *(uint4*)(d_ + blo[NBCH - 2]) = S##b2; *(uint4*)(d_ + blo[NBCH - 1]) = S##b3; } } while (0)
; template <int NJ, class RowA>
; DI void gemm_main(f32x16 (&acc)[2][NJ], const bf16_t* __restrict__ A, RowA rowA, size_t kstrideA, int m0, int Mmax,
;                   const bf16_t* __restrict__ Bt, size_t ldb, int n0, int nk, char* smem) {
;     ...
;   __syncthreads();
;   G_LOAD(x0, 0, 0);
;   G_LOAD(x1, 0, 1);
;   G_STORE(0, x0, 0);
;   __syncthreads();
; #pragma unroll 1
;   for (int kt = 0; kt < nk; kt += 2) {
;     G_LOAD(x0, 0, (kt + 2 < nk ? kt + 2 : nk - 1));
;     G_COMPUTE(0);
;     G_STORE(1, x1, 0);
;     __syncthreads();
;     G_LOAD(x1, 0, (kt + 3 < nk ? kt + 3 : nk - 1));
;     G_COMPUTE(1);
;     G_STORE(0, x0, 0);
;     __syncthreads();
;   }
.LBB0_1956:
	s_cmp_lt_i32 s0, 12
	s_cbranch_scc0 .Lpeel_tail_1956
	ds_read_b128 v[166:169], v0
	ds_read_b128 v[170:173], v139 offset:18432
	ds_read_b128 v[174:177], v139 offset:23040
	ds_read_b128 v[178:181], v0 offset:4608
	s_add_i32 s1, s0, 4
	s_min_u32 s1, s1, 15
	s_lshl_b32 s14, s1, 7
	v_lshl_add_u64 v[98:99], v[122:123], 0, s[14:15]
	v_lshl_add_u64 v[102:103], v[124:125], 0, s[14:15]
	v_lshl_add_u64 v[106:107], v[126:127], 0, s[14:15]
	v_lshl_add_u64 v[110:111], v[128:129], 0, s[14:15]
	v_lshl_add_u64 v[114:115], v[130:131], 0, s[14:15]
	v_lshl_add_u64 v[118:119], v[132:133], 0, s[14:15]
	s_add_i32 s0, s0, 2
	v_lshl_add_u64 v[158:159], v[134:135], 0, s[14:15]
	v_lshl_add_u64 v[160:161], v[136:137], 0, s[14:15]
	s_setprio 1
	ds_read_b128 v[182:185], v0 offset:32
	ds_read_b128 v[186:189], v139 offset:18464
	ds_read_b128 v[190:193], v139 offset:23072
	ds_read_b128 v[194:197], v0 offset:4640
	s_waitcnt lgkmcnt(4)
	v_mfma_f32_32x32x16_bf16 v[50:65], v[166:169], v[170:173], v[50:65]
	global_load_dwordx4 v[98:101], v[98:99], off
	v_mfma_f32_32x32x16_bf16 v[34:49], v[166:169], v[174:177], v[34:49]
	global_load_dwordx4 v[102:105], v[102:103], off
	v_mfma_f32_32x32x16_bf16 v[18:33], v[178:181], v[170:173], v[18:33]
	global_load_dwordx4 v[106:109], v[106:107], off
	v_mfma_f32_32x32x16_bf16 v[2:17], v[178:181], v[174:177], v[2:17]
	global_load_dwordx4 v[110:113], v[110:111], off
	ds_read_b128 v[166:169], v0 offset:64
	ds_read_b128 v[170:173], v139 offset:18496
	ds_read_b128 v[174:177], v139 offset:23104
	ds_read_b128 v[178:181], v0 offset:4672
	s_waitcnt lgkmcnt(4)
	v_mfma_f32_32x32x16_bf16 v[50:65], v[182:185], v[186:189], v[50:65]
	global_load_dwordx4 v[114:117], v[114:115], off
	v_mfma_f32_32x32x16_bf16 v[34:49], v[182:185], v[190:193], v[34:49]
	global_load_dwordx4 v[118:121], v[118:119], off
	v_mfma_f32_32x32x16_bf16 v[18:33], v[194:197], v[186:189], v[18:33]
	global_load_dwordx4 v[146:149], v[160:161], off
	v_mfma_f32_32x32x16_bf16 v[2:17], v[194:197], v[190:193], v[2:17]
	global_load_dwordx4 v[150:153], v[158:159], off
	ds_read_b128 v[182:185], v0 offset:96
	ds_read_b128 v[186:189], v139 offset:18528
	ds_read_b128 v[190:193], v139 offset:23136
	ds_read_b128 v[194:197], v0 offset:4704
	s_waitcnt lgkmcnt(4)
	v_mfma_f32_32x32x16_bf16 v[50:65], v[166:169], v[170:173], v[50:65]
	s_waitcnt vmcnt(8)
	ds_write_b128 v138, v[74:77] offset:36864
	v_mfma_f32_32x32x16_bf16 v[34:49], v[166:169], v[174:177], v[34:49]
	ds_write_b128 v140, v[78:81] offset:36864
	v_mfma_f32_32x32x16_bf16 v[18:33], v[178:181], v[170:173], v[18:33]
	ds_write_b128 v142, v[82:85] offset:36864
	v_mfma_f32_32x32x16_bf16 v[2:17], v[178:181], v[174:177], v[2:17]
	ds_write_b128 v144, v[86:89] offset:36864
	s_waitcnt lgkmcnt(4)
	v_mfma_f32_32x32x16_bf16 v[50:65], v[182:185], v[186:189], v[50:65]
	ds_write_b128 v138, v[90:93] offset:55296
	v_mfma_f32_32x32x16_bf16 v[34:49], v[182:185], v[190:193], v[34:49]
	ds_write_b128 v140, v[94:97] offset:55296
	v_mfma_f32_32x32x16_bf16 v[18:33], v[194:197], v[186:189], v[18:33]
	ds_write_b128 v142, v[66:69] offset:55296
	v_mfma_f32_32x32x16_bf16 v[2:17], v[194:197], v[190:193], v[2:17]
	ds_write_b128 v144, v[70:73] offset:55296
	s_setprio 0
	s_min_u32 s1, s0, 12
	s_lshl_b32 s14, s1, 7
	v_lshl_add_u64 v[66:67], v[122:123], 0, s[14:15]
	v_lshl_add_u64 v[68:69], v[124:125], 0, s[14:15]
	v_lshl_add_u64 v[70:71], v[126:127], 0, s[14:15]
	v_lshl_add_u64 v[72:73], v[128:129], 0, s[14:15]
	v_lshl_add_u64 v[90:91], v[130:131], 0, s[14:15]
	v_lshl_add_u64 v[94:95], v[132:133], 0, s[14:15]
	s_waitcnt lgkmcnt(0)
	s_barrier
	ds_read_b128 v[166:169], v0 offset:36864
	ds_read_b128 v[170:173], v139 offset:55296
	ds_read_b128 v[174:177], v139 offset:59904
	ds_read_b128 v[178:181], v0 offset:41472
	v_lshl_add_u64 v[154:155], v[134:135], 0, s[14:15]
	v_lshl_add_u64 v[156:157], v[136:137], 0, s[14:15]
	s_setprio 1
	ds_read_b128 v[182:185], v0 offset:36896
	ds_read_b128 v[186:189], v139 offset:55328
	ds_read_b128 v[190:193], v139 offset:59936
	ds_read_b128 v[194:197], v0 offset:41504
	s_waitcnt lgkmcnt(4)
	v_mfma_f32_32x32x16_bf16 v[50:65], v[166:169], v[170:173], v[50:65]
	global_load_dwordx4 v[74:77], v[66:67], off offset:384
	v_mfma_f32_32x32x16_bf16 v[34:49], v[166:169], v[174:177], v[34:49]
	global_load_dwordx4 v[78:81], v[68:69], off offset:384
	v_mfma_f32_32x32x16_bf16 v[18:33], v[178:181], v[170:173], v[18:33]
	global_load_dwordx4 v[82:85], v[70:71], off offset:384
	v_mfma_f32_32x32x16_bf16 v[2:17], v[178:181], v[174:177], v[2:17]
	global_load_dwordx4 v[86:89], v[72:73], off offset:384
	ds_read_b128 v[166:169], v0 offset:36928
	ds_read_b128 v[170:173], v139 offset:55360
	ds_read_b128 v[174:177], v139 offset:59968
	ds_read_b128 v[178:181], v0 offset:41536
	s_waitcnt lgkmcnt(4)
	v_mfma_f32_32x32x16_bf16 v[50:65], v[182:185], v[186:189], v[50:65]
	global_load_dwordx4 v[90:93], v[90:91], off offset:384
	v_mfma_f32_32x32x16_bf16 v[34:49], v[182:185], v[190:193], v[34:49]
	global_load_dwordx4 v[94:97], v[94:95], off offset:384
	v_mfma_f32_32x32x16_bf16 v[18:33], v[194:197], v[186:189], v[18:33]
	global_load_dwordx4 v[66:69], v[154:155], off offset:384
	v_mfma_f32_32x32x16_bf16 v[2:17], v[194:197], v[190:193], v[2:17]
	global_load_dwordx4 v[70:73], v[156:157], off offset:384
	ds_read_b128 v[182:185], v0 offset:36960
	ds_read_b128 v[186:189], v139 offset:55392
	ds_read_b128 v[190:193], v139 offset:60000
	ds_read_b128 v[194:197], v0 offset:41568
	s_waitcnt lgkmcnt(4)
	v_mfma_f32_32x32x16_bf16 v[50:65], v[166:169], v[170:173], v[50:65]
	s_waitcnt vmcnt(8)
	ds_write_b128 v138, v[98:101]
	v_mfma_f32_32x32x16_bf16 v[34:49], v[166:169], v[174:177], v[34:49]
	ds_write_b128 v140, v[102:105]
	v_mfma_f32_32x32x16_bf16 v[18:33], v[178:181], v[170:173], v[18:33]
	ds_write_b128 v142, v[106:109]
	v_mfma_f32_32x32x16_bf16 v[2:17], v[178:181], v[174:177], v[2:17]
	ds_write_b128 v144, v[110:113]
	s_waitcnt lgkmcnt(4)
	v_mfma_f32_32x32x16_bf16 v[50:65], v[182:185], v[186:189], v[50:65]
	ds_write_b128 v138, v[114:117] offset:18432
	v_mfma_f32_32x32x16_bf16 v[34:49], v[182:185], v[190:193], v[34:49]
	ds_write_b128 v140, v[118:121] offset:18432
	v_mfma_f32_32x32x16_bf16 v[18:33], v[194:197], v[186:189], v[18:33]
	ds_write_b128 v142, v[150:153] offset:18432
	v_mfma_f32_32x32x16_bf16 v[2:17], v[194:197], v[190:193], v[2:17]
	ds_write_b128 v144, v[146:149] offset:18432
	s_setprio 0
	s_cmp_lt_u32 s0, 14
	s_waitcnt lgkmcnt(0)
	s_barrier
	s_branch .LBB0_1956
; #define G_STORE(ST, S, unused) do { char* d_ = smem + (ST) * STAGE; \
;     *(uint4*)(d_ + alo[0]) = S##a0; *(uint4*)(d_ + alo[1]) = S##a1; *(uint4*)(d_ + alo[2]) = S##a2; *(uint4*)(d_ + alo[3]) = S##a3; \
;     *(uint4*)(d_ + blo[0]) = S##b0; *(uint4*)(d_ + blo[1]) = S##b1; \
;     if (NBCH == 4) { *(uint4*)(d_ + blo[NBCH - 2]) = S##b2; *(uint4*)(d_ + blo[NBCH - 1]) = S##b3; } } while (0)
; template <int NJ, class RowA>
; DI void gemm_main(f32x16 (&acc)[2][NJ], const bf16_t* __restrict__ A, RowA rowA, size_t kstrideA, int m0, int Mmax,
;                   const bf16_t* __restrict__ Bt, size_t ldb, int n0, int nk, char* smem) {
;     ...
;   __syncthreads();
;   G_LOAD(x0, 0, 0);
;   G_LOAD(x1, 0, 1);
;   G_STORE(0, x0, 0);
;   __syncthreads();
; #pragma unroll 1
;   for (int kt = 0; kt < nk; kt += 2) {
;     G_LOAD(x0, 0, (kt + 2 < nk ? kt + 2 : nk - 1));
;     G_COMPUTE(0);
;     G_STORE(1, x1, 0);
;     __syncthreads();
;     G_LOAD(x1, 0, (kt + 3 < nk ? kt + 3 : nk - 1));
;     G_COMPUTE(1);
;     G_STORE(0, x0, 0);
;     __syncthreads();
;   }
.Lpeel_tail_1956:
	ds_read_b128 v[166:169], v0
	ds_read_b128 v[170:173], v139 offset:18432
	ds_read_b128 v[174:177], v139 offset:23040
	ds_read_b128 v[178:181], v0 offset:4608
	s_add_i32 s1, s0, 4
	s_min_u32 s1, s1, 15
	s_lshl_b32 s14, s1, 7
	v_lshl_add_u64 v[98:99], v[122:123], 0, s[14:15]
	v_lshl_add_u64 v[102:103], v[124:125], 0, s[14:15]
	v_lshl_add_u64 v[106:107], v[126:127], 0, s[14:15]
	v_lshl_add_u64 v[110:111], v[128:129], 0, s[14:15]
	v_lshl_add_u64 v[114:115], v[130:131], 0, s[14:15]
	v_lshl_add_u64 v[118:119], v[132:133], 0, s[14:15]
	s_add_i32 s0, s0, 2
	v_lshl_add_u64 v[158:159], v[134:135], 0, s[14:15]
	v_lshl_add_u64 v[160:161], v[136:137], 0, s[14:15]
	s_setprio 1
	ds_read_b128 v[182:185], v0 offset:32
	ds_read_b128 v[186:189], v139 offset:18464
	ds_read_b128 v[190:193], v139 offset:23072
	ds_read_b128 v[194:197], v0 offset:4640
	s_waitcnt lgkmcnt(4)
	v_mfma_f32_32x32x16_bf16 v[50:65], v[166:169], v[170:173], v[50:65]
	v_mfma_f32_32x32x16_bf16 v[34:49], v[166:169], v[174:177], v[34:49]
	v_mfma_f32_32x32x16_bf16 v[18:33], v[178:181], v[170:173], v[18:33]
	v_mfma_f32_32x32x16_bf16 v[2:17], v[178:181], v[174:177], v[2:17]
	ds_read_b128 v[166:169], v0 offset:64
	ds_read_b128 v[170:173], v139 offset:18496
	ds_read_b128 v[174:177], v139 offset:23104
	ds_read_b128 v[178:181], v0 offset:4672
	s_waitcnt lgkmcnt(4)
	v_mfma_f32_32x32x16_bf16 v[50:65], v[182:185], v[186:189], v[50:65]
	v_mfma_f32_32x32x16_bf16 v[34:49], v[182:185], v[190:193], v[34:49]
	v_mfma_f32_32x32x16_bf16 v[18:33], v[194:197], v[186:189], v[18:33]
	v_mfma_f32_32x32x16_bf16 v[2:17], v[194:197], v[190:193], v[2:17]
	ds_read_b128 v[182:185], v0 offset:96
	ds_read_b128 v[186:189], v139 offset:18528
	ds_read_b128 v[190:193], v139 offset:23136
	ds_read_b128 v[194:197], v0 offset:4704
	s_waitcnt lgkmcnt(4)
	v_mfma_f32_32x32x16_bf16 v[50:65], v[166:169], v[170:173], v[50:65]
	s_waitcnt vmcnt(0)
	ds_write_b128 v138, v[74:77] offset:36864
	v_mfma_f32_32x32x16_bf16 v[34:49], v[166:169], v[174:177], v[34:49]
	ds_write_b128 v140, v[78:81] offset:36864
	v_mfma_f32_32x32x16_bf16 v[18:33], v[178:181], v[170:173], v[18:33]
	ds_write_b128 v142, v[82:85] offset:36864
	v_mfma_f32_32x32x16_bf16 v[2:17], v[178:181], v[174:177], v[2:17]
	ds_write_b128 v144, v[86:89] offset:36864
	s_waitcnt lgkmcnt(4)
	v_mfma_f32_32x32x16_bf16 v[50:65], v[182:185], v[186:189], v[50:65]
	ds_write_b128 v138, v[90:93] offset:55296
	v_mfma_f32_32x32x16_bf16 v[34:49], v[182:185], v[190:193], v[34:49]
	ds_write_b128 v140, v[94:97] offset:55296
	v_mfma_f32_32x32x16_bf16 v[18:33], v[194:197], v[186:189], v[18:33]
	ds_write_b128 v142, v[66:69] offset:55296
	v_mfma_f32_32x32x16_bf16 v[2:17], v[194:197], v[190:193], v[2:17]
	ds_write_b128 v144, v[70:73] offset:55296
	s_setprio 0
	s_min_u32 s1, s0, 12
	s_lshl_b32 s14, s1, 7
	v_lshl_add_u64 v[66:67], v[122:123], 0, s[14:15]
	v_lshl_add_u64 v[68:69], v[124:125], 0, s[14:15]
	v_lshl_add_u64 v[70:71], v[126:127], 0, s[14:15]
	v_lshl_add_u64 v[72:73], v[128:129], 0, s[14:15]
	v_lshl_add_u64 v[90:91], v[130:131], 0, s[14:15]
	v_lshl_add_u64 v[94:95], v[132:133], 0, s[14:15]
	s_waitcnt lgkmcnt(0)
	s_barrier
	ds_read_b128 v[166:169], v0 offset:36864
	ds_read_b128 v[170:173], v139 offset:55296
	ds_read_b128 v[174:177], v139 offset:59904
	ds_read_b128 v[178:181], v0 offset:41472
	v_lshl_add_u64 v[154:155], v[134:135], 0, s[14:15]
	v_lshl_add_u64 v[156:157], v[136:137], 0, s[14:15]
	s_setprio 1
	ds_read_b128 v[182:185], v0 offset:36896
	ds_read_b128 v[186:189], v139 offset:55328
	ds_read_b128 v[190:193], v139 offset:59936
	ds_read_b128 v[194:197], v0 offset:41504
	s_waitcnt lgkmcnt(4)
	v_mfma_f32_32x32x16_bf16 v[50:65], v[166:169], v[170:173], v[50:65]
	v_mfma_f32_32x32x16_bf16 v[34:49], v[166:169], v[174:177], v[34:49]
	v_mfma_f32_32x32x16_bf16 v[18:33], v[178:181], v[170:173], v[18:33]
	v_mfma_f32_32x32x16_bf16 v[2:17], v[178:181], v[174:177], v[2:17]
	ds_read_b128 v[166:169], v0 offset:36928
	ds_read_b128 v[170:173], v139 offset:55360
	ds_read_b128 v[174:177], v139 offset:59968
	ds_read_b128 v[178:181], v0 offset:41536
	s_waitcnt lgkmcnt(4)
	v_mfma_f32_32x32x16_bf16 v[50:65], v[182:185], v[186:189], v[50:65]
	v_mfma_f32_32x32x16_bf16 v[34:49], v[182:185], v[190:193], v[34:49]
	v_mfma_f32_32x32x16_bf16 v[18:33], v[194:197], v[186:189], v[18:33]
	v_mfma_f32_32x32x16_bf16 v[2:17], v[194:197], v[190:193], v[2:17]
	ds_read_b128 v[182:185], v0 offset:36960
	ds_read_b128 v[186:189], v139 offset:55392
	ds_read_b128 v[190:193], v139 offset:60000
	ds_read_b128 v[194:197], v0 offset:41568
	s_waitcnt lgkmcnt(4)
	v_mfma_f32_32x32x16_bf16 v[50:65], v[166:169], v[170:173], v[50:65]
	v_mfma_f32_32x32x16_bf16 v[34:49], v[166:169], v[174:177], v[34:49]
	v_mfma_f32_32x32x16_bf16 v[18:33], v[178:181], v[170:173], v[18:33]
	v_mfma_f32_32x32x16_bf16 v[2:17], v[178:181], v[174:177], v[2:17]
	s_waitcnt lgkmcnt(0)
	v_mfma_f32_32x32x16_bf16 v[50:65], v[182:185], v[186:189], v[50:65]
	v_mfma_f32_32x32x16_bf16 v[34:49], v[182:185], v[190:193], v[34:49]
	v_mfma_f32_32x32x16_bf16 v[18:33], v[194:197], v[186:189], v[18:33]
	v_mfma_f32_32x32x16_bf16 v[2:17], v[194:197], v[190:193], v[2:17]
	s_setprio 0
	s_cmp_lt_u32 s0, 14
	s_waitcnt lgkmcnt(0)
	s_barrier
; #define TIDX (tid_launder())
; DI unsigned pack2(float a, float b) { hwf2 v = {a, b}; hwbf2 r = __builtin_convertvector(v, hwbf2); return __builtin_bit_cast(unsigned, r); }
; DI int crow(int reg, int hh) { return (reg & 3) + 8 * (reg >> 2) + 4 * hh; }
; DI float siluf(float x) { return x * __builtin_amdgcn_rcpf(1.f + __expf(-x)); }
; template <int NJ>
; DI void acc_to_ct(const f32x16 (&acc)[2][NJ], float* Ct) {
;   const int lane = TIDX & 63, wid = TIDX >> 6, wm = wid >> 1, wn = wid & 1;
;   const int r = lane & 31, hh = lane >> 5;
; #pragma unroll
;   for (int i = 0; i < 2; ++i)
; #pragma unroll
;     for (int j = 0; j < NJ; ++j)
; #pragma unroll
;       for (int e = 0; e < 16; ++e) Ct[(wm * 64 + i * 32 + crow(e, hh)) * 132 + wn * 32 * NJ + j * 32 + r] = acc[i][j][e];
;   __syncthreads();
; DI void epi_store64(const float* Ct, int cb, const float* rn, int grp, const float* gain, bool silu, const float* bias,
;                     bf16_t* dst, size_t ldd, int dcol0, int m0, int Mmax) {
;   const int tid = TIDX, c = (tid & 15) * 4;
;   float4 gv = make_float4(1.f, 1.f, 1.f, 1.f), bv = make_float4(0.f, 0.f, 0.f, 0.f);
;   if (rn) gv = *(const float4*)(gain + c);
;   if (bias) bv = *(const float4*)(bias + c);
; #pragma unroll
;   for (int q = 0; q < 8; ++q) {
;     const int row = (tid >> 4) + 16 * q;
;     float4 v = *(const float4*)(Ct + row * 132 + cb + c);
;     v.x += bv.x; v.y += bv.y; v.z += bv.z; v.w += bv.w;
;     if (rn) { const float sc = rn[row * 2 + grp]; v.x *= sc * gv.x; v.y *= sc * gv.y; v.z *= sc * gv.z; v.w *= sc * gv.w; }
;     if (silu) { v.x = siluf(v.x); v.y = siluf(v.y); v.z = siluf(v.z); v.w = siluf(v.w); }
;     uint2 o; o.x = pack2(v.x, v.y); o.y = pack2(v.z, v.w);
;     *(uint2*)(dst + (size_t)(m0 + row) * ldd + dcol0 + c) = o;
;   }
	v_mov_b32_e32 v0, v230
	s_waitcnt vmcnt(1)
	v_mov_b32_e32 v66, v230
	v_and_b32_e32 v67, 31, v0
	v_lshrrev_b32_e32 v0, 3, v0
	v_and_b32_e32 v0, 4, v0
	v_lshrrev_b32_e32 v68, 1, v66
	v_and_or_b32 v0, v68, s47, v0
	v_and_or_b32 v66, v66, 64, v67
	v_mul_lo_u32 v0, v0, s79
	v_lshl_add_u32 v0, v66, 2, v0
	ds_write2_b32 v0, v50, v34 offset1:32
	ds_write2_b32 v0, v51, v35 offset0:132 offset1:164
	v_add_u32_e32 v34, 0x400, v0
	ds_write2_b32 v34, v52, v36 offset0:8 offset1:40
	ds_write2_b32 v34, v53, v37 offset0:140 offset1:172
	v_add_u32_e32 v34, 0x1000, v0
	ds_write2_b32 v34, v54, v38 offset0:32 offset1:64
	ds_write2_b32 v34, v55, v39 offset0:164 offset1:196
	v_add_u32_e32 v34, 0x1400, v0
	ds_write2_b32 v34, v56, v40 offset0:40 offset1:72
	ds_write2_b32 v34, v57, v41 offset0:172 offset1:204
	v_add_u32_e32 v34, 0x2000, v0
	ds_write2_b32 v34, v58, v42 offset0:64 offset1:96
	ds_write2_b32 v34, v59, v43 offset0:196 offset1:228
	v_add_u32_e32 v34, 0x2400, v0
	ds_write2_b32 v34, v60, v44 offset0:72 offset1:104
	ds_write2_b32 v34, v61, v45 offset0:204 offset1:236
	v_add_u32_e32 v34, 0x3000, v0
	ds_write2_b32 v34, v62, v46 offset0:96 offset1:128
	v_add_u32_e32 v34, 0x3200, v0
	ds_write2_b32 v34, v63, v47 offset0:100 offset1:132
	v_add_u32_e32 v34, 0x3400, v0
	ds_write2_b32 v34, v64, v48 offset0:104 offset1:136
	v_add_u32_e32 v34, 0x3600, v0
	ds_write2_b32 v34, v65, v49 offset0:108 offset1:140
	v_add_u32_e32 v34, 0x4000, v0
	ds_write2_b32 v34, v18, v2 offset0:128 offset1:160
	v_add_u32_e32 v2, 0x4400, v0
	ds_write2_b32 v2, v19, v3 offset0:4 offset1:36
	ds_write2_b32 v2, v20, v4 offset0:136 offset1:168
	v_add_u32_e32 v2, 0x4800, v0
	ds_write2_b32 v2, v21, v5 offset0:12 offset1:44
	v_add_u32_e32 v2, 0x5000, v0
	ds_write2_b32 v2, v22, v6 offset0:160 offset1:192
	v_add_u32_e32 v2, 0x5400, v0
	ds_write2_b32 v2, v23, v7 offset0:36 offset1:68
	ds_write2_b32 v2, v24, v8 offset0:168 offset1:200
	v_add_u32_e32 v2, 0x5800, v0
	ds_write2_b32 v2, v25, v9 offset0:44 offset1:76
	v_add_u32_e32 v2, 0x6000, v0
	ds_write2_b32 v2, v26, v10 offset0:192 offset1:224
	v_add_u32_e32 v2, 0x6400, v0
	ds_write2_b32 v2, v27, v11 offset0:68 offset1:100
	ds_write2_b32 v2, v28, v12 offset0:200 offset1:232
	v_add_u32_e32 v2, 0x6800, v0
	ds_write2_b32 v2, v29, v13 offset0:76 offset1:108
	v_add_u32_e32 v2, 0x7200, v0
	ds_write2_b32 v2, v30, v14 offset0:96 offset1:128
	v_add_u32_e32 v2, 0x7400, v0
	ds_write2_b32 v2, v31, v15 offset0:100 offset1:132
	v_add_u32_e32 v2, 0x7600, v0
	v_add_u32_e32 v0, 0x7800, v0
	s_cmp_gt_i32 s12, 3
	s_mov_b64 s[0:1], -1
	ds_write2_b32 v2, v32, v16 offset0:104 offset1:136
	ds_write2_b32 v0, v33, v17 offset0:108 offset1:140
	s_waitcnt lgkmcnt(0)
	s_barrier
	s_cbranch_scc0 .LBB0_2086
	s_cmp_lg_u32 s12, 4
	s_cbranch_scc0 .LBB0_2045
	s_cmp_gt_u32 s12, 8
	s_cbranch_scc0 .LBB0_2042
	s_ashr_i32 s0, s3, 7
	s_add_i32 s4, s0, s4
	s_ashr_i32 s0, s11, 31
	s_lshr_b32 s0, s0, 21
	s_add_i32 s0, s11, s0
	s_and_b32 s0, s0, 0xfffff800
	s_sub_i32 s13, s11, s0
	s_cmp_lt_i32 s12, 11
	s_mov_b64 s[0:1], -1
	s_cbranch_scc1 .LBB0_2012
	s_cmp_lt_i32 s12, 12
	s_cbranch_scc1 .LBB0_1982
	s_cmp_lg_u32 s12, 12
	s_cbranch_scc0 .LBB0_1968
	s_cmp_gt_u32 s12, 24
	s_mov_b32 s3, s15
	s_cbranch_scc0 .LBB0_1965
	v_mov_b32_e32 v0, v230
	v_readlane_b32 s16, v252, 57
	s_lshl_b64 s[0:1], s[2:3], 1
	v_lshlrev_b32_e32 v2, 2, v0
	v_readlane_b32 s28, v253, 5
	v_and_b32_e32 v4, 60, v2
	v_readlane_b32 s29, v253, 6
	s_add_u32 s0, s28, s0
	v_ashrrev_i32_e32 v10, 4, v0
	s_addc_u32 s1, s29, s1
	v_lshlrev_b32_e32 v0, 1, v4
	v_lshl_add_u64 v[2:3], s[0:1], 0, v[0:1]
	v_mul_lo_u32 v0, v10, s79
	v_lshl_add_u32 v0, v4, 2, v0
	ds_read_b128 v[4:7], v0
	s_movk_i32 s6, 0xe700
	s_mov_b32 s7, -1
	v_lshl_add_u64 v[2:3], v[2:3], 0, s[6:7]
	v_readlane_b32 s17, v252, 58
	s_waitcnt lgkmcnt(0)
	v_pk_add_f32 v[4:5], v[4:5], 0 op_sel_hi:[1,0]
	v_pk_add_f32 v[6:7], v[6:7], 0 op_sel_hi:[1,0]
	v_mul_f32_e32 v8, 0xbfb8aa3b, v4
	v_mul_f32_e32 v9, 0xbfb8aa3b, v5
	v_exp_f32_e32 v8, v8
	v_exp_f32_e32 v9, v9
	v_readlane_b32 s18, v252, 59
	v_readlane_b32 s19, v252, 60
	v_add_f32_e32 v8, 1.0, v8
	v_add_f32_e32 v9, 1.0, v9
	v_rcp_f32_e32 v8, v8
	v_rcp_f32_e32 v9, v9
	v_readlane_b32 s20, v252, 61
	v_readlane_b32 s21, v252, 62
	v_readlane_b32 s22, v252, 63
	v_pk_mul_f32 v[4:5], v[4:5], v[8:9]
	v_mul_f32_e32 v8, 0xbfb8aa3b, v6
	v_mul_f32_e32 v9, 0xbfb8aa3b, v7
	v_exp_f32_e32 v8, v8
	v_exp_f32_e32 v9, v9
	v_readlane_b32 s23, v253, 0
	v_readlane_b32 s24, v253, 1
	v_add_f32_e32 v8, 1.0, v8
	v_add_f32_e32 v9, 1.0, v9
	v_rcp_f32_e32 v8, v8
	v_rcp_f32_e32 v9, v9
	v_readlane_b32 s25, v253, 2
	v_readlane_b32 s26, v253, 3
	v_readlane_b32 s27, v253, 4
	v_pk_mul_f32 v[6:7], v[6:7], v[8:9]
	v_cvt_pk_bf16_f32 v8, v4, v5
	v_add_u32_e32 v4, s11, v10
	v_ashrrev_i32_e32 v5, 31, v4
	v_cvt_pk_bf16_f32 v9, v6, v7
	v_lshlrev_b64 v[6:7], 11, v[4:5]
	v_lshl_add_u64 v[6:7], v[2:3], 0, v[6:7]
	global_store_dwordx2 v[6:7], v[8:9], off
	ds_read_b128 v[6:9], v0 offset:8448
	v_readlane_b32 s30, v253, 7
	v_readlane_b32 s31, v253, 8
	s_waitcnt lgkmcnt(0)
	v_pk_add_f32 v[6:7], v[6:7], 0 op_sel_hi:[1,0]
	s_nop 0
	v_mul_f32_e32 v5, 0xbfb8aa3b, v6
	v_exp_f32_e32 v5, v5
	v_pk_add_f32 v[8:9], v[8:9], 0 op_sel_hi:[1,0]
	v_add_f32_e32 v5, 1.0, v5
	v_rcp_f32_e32 v10, v5
	v_mul_f32_e32 v5, 0xbfb8aa3b, v7
	v_exp_f32_e32 v5, v5
	s_nop 0
	v_add_f32_e32 v5, 1.0, v5
	v_rcp_f32_e32 v11, v5
	v_mul_f32_e32 v5, 0xbfb8aa3b, v8
	v_exp_f32_e32 v5, v5
	v_pk_mul_f32 v[6:7], v[6:7], v[10:11]
	s_nop 0
	v_cvt_pk_bf16_f32 v6, v6, v7
	v_add_f32_e32 v5, 1.0, v5
	v_rcp_f32_e32 v10, v5
	v_mul_f32_e32 v5, 0xbfb8aa3b, v9
	v_exp_f32_e32 v5, v5
	s_nop 0
	v_add_f32_e32 v5, 1.0, v5
	v_rcp_f32_e32 v11, v5
	s_nop 0
	v_pk_mul_f32 v[8:9], v[8:9], v[10:11]
	s_nop 0
	v_cvt_pk_bf16_f32 v7, v8, v9
	v_add_u32_e32 v8, 16, v4
	v_ashrrev_i32_e32 v9, 31, v8
	v_lshlrev_b64 v[8:9], 11, v[8:9]
	v_lshl_add_u64 v[8:9], v[2:3], 0, v[8:9]
	global_store_dwordx2 v[8:9], v[6:7], off
	ds_read_b128 v[6:9], v0 offset:16896
	s_waitcnt lgkmcnt(0)
; #define TIDX (tid_launder())
; DI unsigned pack2(float a, float b) { hwf2 v = {a, b}; hwbf2 r = __builtin_convertvector(v, hwbf2); return __builtin_bit_cast(unsigned, r); }
; DI float siluf(float x) { return x * __builtin_amdgcn_rcpf(1.f + __expf(-x)); }
; DI void epi_store64(const float* Ct, int cb, const float* rn, int grp, const float* gain, bool silu, const float* bias,
;                     bf16_t* dst, size_t ldd, int dcol0, int m0, int Mmax) {
;   const int tid = TIDX, c = (tid & 15) * 4;
;   float4 gv = make_float4(1.f, 1.f, 1.f, 1.f), bv = make_float4(0.f, 0.f, 0.f, 0.f);
;   if (rn) gv = *(const float4*)(gain + c);
;   if (bias) bv = *(const float4*)(bias + c);
; #pragma unroll
;   for (int q = 0; q < 8; ++q) {
;     const int row = (tid >> 4) + 16 * q;
;     float4 v = *(const float4*)(Ct + row * 132 + cb + c);
;     v.x += bv.x; v.y += bv.y; v.z += bv.z; v.w += bv.w;
;     if (rn) { const float sc = rn[row * 2 + grp]; v.x *= sc * gv.x; v.y *= sc * gv.y; v.z *= sc * gv.z; v.w *= sc * gv.w; }
;     if (silu) { v.x = siluf(v.x); v.y = siluf(v.y); v.z = siluf(v.z); v.w = siluf(v.w); }
;     uint2 o; o.x = pack2(v.x, v.y); o.y = pack2(v.z, v.w);
;     *(uint2*)(dst + (size_t)(m0 + row) * ldd + dcol0 + c) = o;
;   }
	v_pk_add_f32 v[6:7], v[6:7], 0 op_sel_hi:[1,0]
	s_nop 0
	v_mul_f32_e32 v5, 0xbfb8aa3b, v6
	v_exp_f32_e32 v5, v5
	v_pk_add_f32 v[8:9], v[8:9], 0 op_sel_hi:[1,0]
	v_add_f32_e32 v5, 1.0, v5
	v_rcp_f32_e32 v10, v5
	v_mul_f32_e32 v5, 0xbfb8aa3b, v7
	v_exp_f32_e32 v5, v5
	s_nop 0
	v_add_f32_e32 v5, 1.0, v5
	v_rcp_f32_e32 v11, v5
	v_mul_f32_e32 v5, 0xbfb8aa3b, v8
	v_exp_f32_e32 v5, v5
	v_pk_mul_f32 v[6:7], v[6:7], v[10:11]
	s_nop 0
	v_cvt_pk_bf16_f32 v6, v6, v7
	v_add_f32_e32 v5, 1.0, v5
	v_rcp_f32_e32 v10, v5
	v_mul_f32_e32 v5, 0xbfb8aa3b, v9
	v_exp_f32_e32 v5, v5
	s_nop 0
	v_add_f32_e32 v5, 1.0, v5
	v_rcp_f32_e32 v11, v5
	s_nop 0
	v_pk_mul_f32 v[8:9], v[8:9], v[10:11]
	s_nop 0
	v_cvt_pk_bf16_f32 v7, v8, v9
	v_add_u32_e32 v8, 32, v4
	v_ashrrev_i32_e32 v9, 31, v8
	v_lshlrev_b64 v[8:9], 11, v[8:9]
	v_lshl_add_u64 v[8:9], v[2:3], 0, v[8:9]
	global_store_dwordx2 v[8:9], v[6:7], off
	ds_read_b128 v[6:9], v0 offset:25344
	s_waitcnt lgkmcnt(0)
	v_pk_add_f32 v[6:7], v[6:7], 0 op_sel_hi:[1,0]
	s_nop 0
	v_mul_f32_e32 v5, 0xbfb8aa3b, v6
	v_exp_f32_e32 v5, v5
	v_pk_add_f32 v[8:9], v[8:9], 0 op_sel_hi:[1,0]
	v_add_f32_e32 v5, 1.0, v5
	v_rcp_f32_e32 v10, v5
	v_mul_f32_e32 v5, 0xbfb8aa3b, v7
	v_exp_f32_e32 v5, v5
	s_nop 0
	v_add_f32_e32 v5, 1.0, v5
	v_rcp_f32_e32 v11, v5
	v_mul_f32_e32 v5, 0xbfb8aa3b, v8
	v_exp_f32_e32 v5, v5
	v_pk_mul_f32 v[6:7], v[6:7], v[10:11]
	s_nop 0
	v_cvt_pk_bf16_f32 v6, v6, v7
	v_add_f32_e32 v5, 1.0, v5
	v_rcp_f32_e32 v10, v5
	v_mul_f32_e32 v5, 0xbfb8aa3b, v9
	v_exp_f32_e32 v5, v5
	s_nop 0
	v_add_f32_e32 v5, 1.0, v5
	v_rcp_f32_e32 v11, v5
	s_nop 0
	v_pk_mul_f32 v[8:9], v[8:9], v[10:11]
	s_nop 0
	v_cvt_pk_bf16_f32 v7, v8, v9
	v_add_u32_e32 v8, 48, v4
	v_ashrrev_i32_e32 v9, 31, v8
	v_lshlrev_b64 v[8:9], 11, v[8:9]
	v_lshl_add_u64 v[8:9], v[2:3], 0, v[8:9]
	global_store_dwordx2 v[8:9], v[6:7], off
	ds_read_b128 v[6:9], v0 offset:33792
	s_waitcnt lgkmcnt(0)
	v_pk_add_f32 v[6:7], v[6:7], 0 op_sel_hi:[1,0]
	s_nop 0
	v_mul_f32_e32 v5, 0xbfb8aa3b, v6
	v_exp_f32_e32 v5, v5
	v_pk_add_f32 v[8:9], v[8:9], 0 op_sel_hi:[1,0]
	v_add_f32_e32 v5, 1.0, v5
	v_rcp_f32_e32 v10, v5
	v_mul_f32_e32 v5, 0xbfb8aa3b, v7
	v_exp_f32_e32 v5, v5
	s_nop 0
	v_add_f32_e32 v5, 1.0, v5
	v_rcp_f32_e32 v11, v5
	v_mul_f32_e32 v5, 0xbfb8aa3b, v8
	v_exp_f32_e32 v5, v5
	v_pk_mul_f32 v[6:7], v[6:7], v[10:11]
	s_nop 0
	v_cvt_pk_bf16_f32 v6, v6, v7
	v_add_f32_e32 v5, 1.0, v5
	v_rcp_f32_e32 v10, v5
	v_mul_f32_e32 v5, 0xbfb8aa3b, v9
	v_exp_f32_e32 v5, v5
	s_nop 0
	v_add_f32_e32 v5, 1.0, v5
	v_rcp_f32_e32 v11, v5
	s_nop 0
	v_pk_mul_f32 v[8:9], v[8:9], v[10:11]
	s_nop 0
	v_cvt_pk_bf16_f32 v7, v8, v9
	v_add_u32_e32 v8, 64, v4
	v_ashrrev_i32_e32 v9, 31, v8
	v_lshlrev_b64 v[8:9], 11, v[8:9]
	v_lshl_add_u64 v[8:9], v[2:3], 0, v[8:9]
	global_store_dwordx2 v[8:9], v[6:7], off
	ds_read_b128 v[6:9], v0 offset:42240
	s_waitcnt lgkmcnt(0)
	v_pk_add_f32 v[6:7], v[6:7], 0 op_sel_hi:[1,0]
	s_nop 0
	v_mul_f32_e32 v5, 0xbfb8aa3b, v6
	v_exp_f32_e32 v5, v5
	v_pk_add_f32 v[8:9], v[8:9], 0 op_sel_hi:[1,0]
	v_add_f32_e32 v5, 1.0, v5
	v_rcp_f32_e32 v10, v5
	v_mul_f32_e32 v5, 0xbfb8aa3b, v7
	v_exp_f32_e32 v5, v5
	s_nop 0
	v_add_f32_e32 v5, 1.0, v5
	v_rcp_f32_e32 v11, v5
	v_mul_f32_e32 v5, 0xbfb8aa3b, v8
	v_exp_f32_e32 v5, v5
	v_pk_mul_f32 v[6:7], v[6:7], v[10:11]
	s_nop 0
	v_cvt_pk_bf16_f32 v6, v6, v7
	v_add_f32_e32 v5, 1.0, v5
	v_rcp_f32_e32 v10, v5
	v_mul_f32_e32 v5, 0xbfb8aa3b, v9
	v_exp_f32_e32 v5, v5
	s_nop 0
	v_add_f32_e32 v5, 1.0, v5
	v_rcp_f32_e32 v11, v5
	s_nop 0
	v_pk_mul_f32 v[8:9], v[8:9], v[10:11]
	s_nop 0
	v_cvt_pk_bf16_f32 v7, v8, v9
	v_add_u32_e32 v8, 0x50, v4
	v_ashrrev_i32_e32 v9, 31, v8
	v_lshlrev_b64 v[8:9], 11, v[8:9]
	v_lshl_add_u64 v[8:9], v[2:3], 0, v[8:9]
	global_store_dwordx2 v[8:9], v[6:7], off
	ds_read_b128 v[6:9], v0 offset:50688
	s_waitcnt lgkmcnt(0)
	v_pk_add_f32 v[6:7], v[6:7], 0 op_sel_hi:[1,0]
	s_nop 0
	v_mul_f32_e32 v5, 0xbfb8aa3b, v6
	v_exp_f32_e32 v5, v5
	v_pk_add_f32 v[8:9], v[8:9], 0 op_sel_hi:[1,0]
	v_add_f32_e32 v5, 1.0, v5
	v_rcp_f32_e32 v10, v5
	v_mul_f32_e32 v5, 0xbfb8aa3b, v7
	v_exp_f32_e32 v5, v5
	s_nop 0
	v_add_f32_e32 v5, 1.0, v5
	v_rcp_f32_e32 v11, v5
	v_mul_f32_e32 v5, 0xbfb8aa3b, v8
	v_exp_f32_e32 v5, v5
	v_pk_mul_f32 v[6:7], v[6:7], v[10:11]
	s_nop 0
	v_cvt_pk_bf16_f32 v6, v6, v7
	v_add_f32_e32 v5, 1.0, v5
	v_rcp_f32_e32 v10, v5
	v_mul_f32_e32 v5, 0xbfb8aa3b, v9
	v_exp_f32_e32 v5, v5
	s_nop 0
	v_add_f32_e32 v5, 1.0, v5
	v_rcp_f32_e32 v11, v5
	s_nop 0
	v_pk_mul_f32 v[8:9], v[8:9], v[10:11]
	s_nop 0
	v_cvt_pk_bf16_f32 v7, v8, v9
	v_add_u32_e32 v8, 0x60, v4
	v_ashrrev_i32_e32 v9, 31, v8
	v_lshlrev_b64 v[8:9], 11, v[8:9]
	v_lshl_add_u64 v[8:9], v[2:3], 0, v[8:9]
	global_store_dwordx2 v[8:9], v[6:7], off
	ds_read_b128 v[6:9], v0 offset:59136
	v_add_u32_e32 v4, 0x70, v4
	v_ashrrev_i32_e32 v5, 31, v4
	v_lshlrev_b64 v[4:5], 11, v[4:5]
	v_lshl_add_u64 v[2:3], v[2:3], 0, v[4:5]
	s_waitcnt lgkmcnt(0)
	v_pk_add_f32 v[6:7], v[6:7], 0 op_sel_hi:[1,0]
	v_pk_add_f32 v[8:9], v[8:9], 0 op_sel_hi:[1,0]
	v_mul_f32_e32 v0, 0xbfb8aa3b, v6
	v_exp_f32_e32 v0, v0
	s_nop 0
	v_add_f32_e32 v0, 1.0, v0
	v_rcp_f32_e32 v10, v0
	v_mul_f32_e32 v0, 0xbfb8aa3b, v7
	v_exp_f32_e32 v0, v0
	s_nop 0
	v_add_f32_e32 v0, 1.0, v0
	v_rcp_f32_e32 v11, v0
	v_mul_f32_e32 v0, 0xbfb8aa3b, v8
	v_exp_f32_e32 v0, v0
	v_pk_mul_f32 v[6:7], v[6:7], v[10:11]
	s_nop 0
	v_cvt_pk_bf16_f32 v6, v6, v7
	v_add_f32_e32 v0, 1.0, v0
	v_rcp_f32_e32 v10, v0
	v_mul_f32_e32 v0, 0xbfb8aa3b, v9
	v_exp_f32_e32 v0, v0
	s_nop 0
	v_add_f32_e32 v0, 1.0, v0
	v_rcp_f32_e32 v11, v0
	v_mov_b32_e32 v0, v230
	v_pk_mul_f32 v[8:9], v[8:9], v[10:11]
	s_nop 0
	v_cvt_pk_bf16_f32 v7, v8, v9
	global_store_dwordx2 v[2:3], v[6:7], off
	s_nop 0
	v_lshlrev_b32_e32 v2, 2, v0
	v_and_b32_e32 v4, 60, v2
	v_ashrrev_i32_e32 v10, 4, v0
	v_lshlrev_b32_e32 v0, 1, v4
	v_lshl_add_u64 v[2:3], s[0:1], 0, v[0:1]
	v_mul_lo_u32 v0, v10, s79
	v_lshl_add_u32 v0, v4, 2, v0
	ds_read_b128 v[4:7], v0 offset:256
	s_movk_i32 s0, 0xe780
	s_mov_b32 s1, -1
	v_lshl_add_u64 v[2:3], v[2:3], 0, s[0:1]
	s_mov_b64 s[0:1], 0
	s_waitcnt lgkmcnt(0)
; #define TIDX (tid_launder())
; DI unsigned pack2(float a, float b) { hwf2 v = {a, b}; hwbf2 r = __builtin_convertvector(v, hwbf2); return __builtin_bit_cast(unsigned, r); }
; DI float siluf(float x) { return x * __builtin_amdgcn_rcpf(1.f + __expf(-x)); }
; DI void epi_store64(const float* Ct, int cb, const float* rn, int grp, const float* gain, bool silu, const float* bias,
;                     bf16_t* dst, size_t ldd, int dcol0, int m0, int Mmax) {
;   const int tid = TIDX, c = (tid & 15) * 4;
;   float4 gv = make_float4(1.f, 1.f, 1.f, 1.f), bv = make_float4(0.f, 0.f, 0.f, 0.f);
;   if (rn) gv = *(const float4*)(gain + c);
;   if (bias) bv = *(const float4*)(bias + c);
; #pragma unroll
;   for (int q = 0; q < 8; ++q) {
;     const int row = (tid >> 4) + 16 * q;
;     float4 v = *(const float4*)(Ct + row * 132 + cb + c);
;     v.x += bv.x; v.y += bv.y; v.z += bv.z; v.w += bv.w;
;     if (rn) { const float sc = rn[row * 2 + grp]; v.x *= sc * gv.x; v.y *= sc * gv.y; v.z *= sc * gv.z; v.w *= sc * gv.w; }
;     if (silu) { v.x = siluf(v.x); v.y = siluf(v.y); v.z = siluf(v.z); v.w = siluf(v.w); }
;     uint2 o; o.x = pack2(v.x, v.y); o.y = pack2(v.z, v.w);
;     *(uint2*)(dst + (size_t)(m0 + row) * ldd + dcol0 + c) = o;
;   }
	v_pk_add_f32 v[4:5], v[4:5], 0 op_sel_hi:[1,0]
	v_pk_add_f32 v[6:7], v[6:7], 0 op_sel_hi:[1,0]
	v_mul_f32_e32 v8, 0xbfb8aa3b, v4
	v_mul_f32_e32 v9, 0xbfb8aa3b, v5
	v_exp_f32_e32 v8, v8
	v_exp_f32_e32 v9, v9
	v_add_f32_e32 v8, 1.0, v8
	v_add_f32_e32 v9, 1.0, v9
	v_rcp_f32_e32 v8, v8
	v_rcp_f32_e32 v9, v9
	s_nop 0
	v_pk_mul_f32 v[4:5], v[4:5], v[8:9]
	v_mul_f32_e32 v8, 0xbfb8aa3b, v6
	v_mul_f32_e32 v9, 0xbfb8aa3b, v7
	v_exp_f32_e32 v8, v8
	v_exp_f32_e32 v9, v9
	v_add_f32_e32 v8, 1.0, v8
	v_add_f32_e32 v9, 1.0, v9
	v_rcp_f32_e32 v8, v8
	v_rcp_f32_e32 v9, v9
	s_nop 0
	v_pk_mul_f32 v[6:7], v[6:7], v[8:9]
	v_cvt_pk_bf16_f32 v8, v4, v5
	v_add_u32_e32 v4, s11, v10
	v_ashrrev_i32_e32 v5, 31, v4
	v_cvt_pk_bf16_f32 v9, v6, v7
	v_lshlrev_b64 v[6:7], 11, v[4:5]
	v_lshl_add_u64 v[6:7], v[2:3], 0, v[6:7]
	global_store_dwordx2 v[6:7], v[8:9], off
	ds_read_b128 v[6:9], v0 offset:8704
	s_waitcnt lgkmcnt(0)
	v_pk_add_f32 v[6:7], v[6:7], 0 op_sel_hi:[1,0]
	s_nop 0
	v_mul_f32_e32 v5, 0xbfb8aa3b, v6
	v_exp_f32_e32 v5, v5
	v_pk_add_f32 v[8:9], v[8:9], 0 op_sel_hi:[1,0]
	v_add_f32_e32 v5, 1.0, v5
	v_rcp_f32_e32 v10, v5
	v_mul_f32_e32 v5, 0xbfb8aa3b, v7
	v_exp_f32_e32 v5, v5
	s_nop 0
	v_add_f32_e32 v5, 1.0, v5
	v_rcp_f32_e32 v11, v5
	v_mul_f32_e32 v5, 0xbfb8aa3b, v8
	v_exp_f32_e32 v5, v5
	v_pk_mul_f32 v[6:7], v[6:7], v[10:11]
	s_nop 0
	v_cvt_pk_bf16_f32 v6, v6, v7
	v_add_f32_e32 v5, 1.0, v5
	v_rcp_f32_e32 v10, v5
	v_mul_f32_e32 v5, 0xbfb8aa3b, v9
	v_exp_f32_e32 v5, v5
	s_nop 0
	v_add_f32_e32 v5, 1.0, v5
	v_rcp_f32_e32 v11, v5
	s_nop 0
	v_pk_mul_f32 v[8:9], v[8:9], v[10:11]
	s_nop 0
	v_cvt_pk_bf16_f32 v7, v8, v9
	v_add_u32_e32 v8, 16, v4
	v_ashrrev_i32_e32 v9, 31, v8
	v_lshlrev_b64 v[8:9], 11, v[8:9]
	v_lshl_add_u64 v[8:9], v[2:3], 0, v[8:9]
	global_store_dwordx2 v[8:9], v[6:7], off
	ds_read_b128 v[6:9], v0 offset:17152
	s_waitcnt lgkmcnt(0)
	v_pk_add_f32 v[6:7], v[6:7], 0 op_sel_hi:[1,0]
	s_nop 0
	v_mul_f32_e32 v5, 0xbfb8aa3b, v6
	v_exp_f32_e32 v5, v5
	v_pk_add_f32 v[8:9], v[8:9], 0 op_sel_hi:[1,0]
	v_add_f32_e32 v5, 1.0, v5
	v_rcp_f32_e32 v10, v5
	v_mul_f32_e32 v5, 0xbfb8aa3b, v7
	v_exp_f32_e32 v5, v5
	s_nop 0
	v_add_f32_e32 v5, 1.0, v5
	v_rcp_f32_e32 v11, v5
	v_mul_f32_e32 v5, 0xbfb8aa3b, v8
	v_exp_f32_e32 v5, v5
	v_pk_mul_f32 v[6:7], v[6:7], v[10:11]
	s_nop 0
	v_cvt_pk_bf16_f32 v6, v6, v7
	v_add_f32_e32 v5, 1.0, v5
	v_rcp_f32_e32 v10, v5
	v_mul_f32_e32 v5, 0xbfb8aa3b, v9
	v_exp_f32_e32 v5, v5
	s_nop 0
	v_add_f32_e32 v5, 1.0, v5
	v_rcp_f32_e32 v11, v5
	s_nop 0
	v_pk_mul_f32 v[8:9], v[8:9], v[10:11]
	s_nop 0
	v_cvt_pk_bf16_f32 v7, v8, v9
	v_add_u32_e32 v8, 32, v4
	v_ashrrev_i32_e32 v9, 31, v8
	v_lshlrev_b64 v[8:9], 11, v[8:9]
	v_lshl_add_u64 v[8:9], v[2:3], 0, v[8:9]
	global_store_dwordx2 v[8:9], v[6:7], off
	ds_read_b128 v[6:9], v0 offset:25600
	s_waitcnt lgkmcnt(0)
	v_pk_add_f32 v[6:7], v[6:7], 0 op_sel_hi:[1,0]
	s_nop 0
	v_mul_f32_e32 v5, 0xbfb8aa3b, v6
	v_exp_f32_e32 v5, v5
	v_pk_add_f32 v[8:9], v[8:9], 0 op_sel_hi:[1,0]
	v_add_f32_e32 v5, 1.0, v5
	v_rcp_f32_e32 v10, v5
	v_mul_f32_e32 v5, 0xbfb8aa3b, v7
	v_exp_f32_e32 v5, v5
	s_nop 0
	v_add_f32_e32 v5, 1.0, v5
	v_rcp_f32_e32 v11, v5
	v_mul_f32_e32 v5, 0xbfb8aa3b, v8
	v_exp_f32_e32 v5, v5
	v_pk_mul_f32 v[6:7], v[6:7], v[10:11]
	s_nop 0
	v_cvt_pk_bf16_f32 v6, v6, v7
	v_add_f32_e32 v5, 1.0, v5
	v_rcp_f32_e32 v10, v5
	v_mul_f32_e32 v5, 0xbfb8aa3b, v9
	v_exp_f32_e32 v5, v5
	s_nop 0
	v_add_f32_e32 v5, 1.0, v5
	v_rcp_f32_e32 v11, v5
	s_nop 0
	v_pk_mul_f32 v[8:9], v[8:9], v[10:11]
	s_nop 0
	v_cvt_pk_bf16_f32 v7, v8, v9
	v_add_u32_e32 v8, 48, v4
	v_ashrrev_i32_e32 v9, 31, v8
	v_lshlrev_b64 v[8:9], 11, v[8:9]
	v_lshl_add_u64 v[8:9], v[2:3], 0, v[8:9]
	global_store_dwordx2 v[8:9], v[6:7], off
	ds_read_b128 v[6:9], v0 offset:34048
	s_waitcnt lgkmcnt(0)
; #define TIDX (tid_launder())
; DI unsigned pack2(float a, float b) { hwf2 v = {a, b}; hwbf2 r = __builtin_convertvector(v, hwbf2); return __builtin_bit_cast(unsigned, r); }
; DI float siluf(float x) { return x * __builtin_amdgcn_rcpf(1.f + __expf(-x)); }
; DI void epi_store64(const float* Ct, int cb, const float* rn, int grp, const float* gain, bool silu, const float* bias,
;                     bf16_t* dst, size_t ldd, int dcol0, int m0, int Mmax) {
;   const int tid = TIDX, c = (tid & 15) * 4;
;   float4 gv = make_float4(1.f, 1.f, 1.f, 1.f), bv = make_float4(0.f, 0.f, 0.f, 0.f);
;   if (rn) gv = *(const float4*)(gain + c);
;   if (bias) bv = *(const float4*)(bias + c);
; #pragma unroll
;   for (int q = 0; q < 8; ++q) {
;     const int row = (tid >> 4) + 16 * q;
;     float4 v = *(const float4*)(Ct + row * 132 + cb + c);
;     v.x += bv.x; v.y += bv.y; v.z += bv.z; v.w += bv.w;
;     if (rn) { const float sc = rn[row * 2 + grp]; v.x *= sc * gv.x; v.y *= sc * gv.y; v.z *= sc * gv.z; v.w *= sc * gv.w; }
;     if (silu) { v.x = siluf(v.x); v.y = siluf(v.y); v.z = siluf(v.z); v.w = siluf(v.w); }
;     uint2 o; o.x = pack2(v.x, v.y); o.y = pack2(v.z, v.w);
;     *(uint2*)(dst + (size_t)(m0 + row) * ldd + dcol0 + c) = o;
;   }
	v_pk_add_f32 v[6:7], v[6:7], 0 op_sel_hi:[1,0]
	s_nop 0
	v_mul_f32_e32 v5, 0xbfb8aa3b, v6
	v_exp_f32_e32 v5, v5
	v_pk_add_f32 v[8:9], v[8:9], 0 op_sel_hi:[1,0]
	v_add_f32_e32 v5, 1.0, v5
	v_rcp_f32_e32 v10, v5
	v_mul_f32_e32 v5, 0xbfb8aa3b, v7
	v_exp_f32_e32 v5, v5
	s_nop 0
	v_add_f32_e32 v5, 1.0, v5
	v_rcp_f32_e32 v11, v5
	v_mul_f32_e32 v5, 0xbfb8aa3b, v8
	v_exp_f32_e32 v5, v5
	v_pk_mul_f32 v[6:7], v[6:7], v[10:11]
	s_nop 0
	v_cvt_pk_bf16_f32 v6, v6, v7
	v_add_f32_e32 v5, 1.0, v5
	v_rcp_f32_e32 v10, v5
	v_mul_f32_e32 v5, 0xbfb8aa3b, v9
	v_exp_f32_e32 v5, v5
	s_nop 0
	v_add_f32_e32 v5, 1.0, v5
	v_rcp_f32_e32 v11, v5
	s_nop 0
	v_pk_mul_f32 v[8:9], v[8:9], v[10:11]
	s_nop 0
	v_cvt_pk_bf16_f32 v7, v8, v9
	v_add_u32_e32 v8, 64, v4
	v_ashrrev_i32_e32 v9, 31, v8
	v_lshlrev_b64 v[8:9], 11, v[8:9]
	v_lshl_add_u64 v[8:9], v[2:3], 0, v[8:9]
	global_store_dwordx2 v[8:9], v[6:7], off
	ds_read_b128 v[6:9], v0 offset:42496
	s_waitcnt lgkmcnt(0)
	v_pk_add_f32 v[6:7], v[6:7], 0 op_sel_hi:[1,0]
	s_nop 0
	v_mul_f32_e32 v5, 0xbfb8aa3b, v6
	v_exp_f32_e32 v5, v5
	v_pk_add_f32 v[8:9], v[8:9], 0 op_sel_hi:[1,0]
	v_add_f32_e32 v5, 1.0, v5
	v_rcp_f32_e32 v10, v5
	v_mul_f32_e32 v5, 0xbfb8aa3b, v7
	v_exp_f32_e32 v5, v5
	s_nop 0
	v_add_f32_e32 v5, 1.0, v5
	v_rcp_f32_e32 v11, v5
	v_mul_f32_e32 v5, 0xbfb8aa3b, v8
	v_exp_f32_e32 v5, v5
	v_pk_mul_f32 v[6:7], v[6:7], v[10:11]
	s_nop 0
	v_cvt_pk_bf16_f32 v6, v6, v7
	v_add_f32_e32 v5, 1.0, v5
	v_rcp_f32_e32 v10, v5
	v_mul_f32_e32 v5, 0xbfb8aa3b, v9
	v_exp_f32_e32 v5, v5
	s_nop 0
	v_add_f32_e32 v5, 1.0, v5
	v_rcp_f32_e32 v11, v5
	s_nop 0
	v_pk_mul_f32 v[8:9], v[8:9], v[10:11]
	s_nop 0
	v_cvt_pk_bf16_f32 v7, v8, v9
	v_add_u32_e32 v8, 0x50, v4
	v_ashrrev_i32_e32 v9, 31, v8
	v_lshlrev_b64 v[8:9], 11, v[8:9]
	v_lshl_add_u64 v[8:9], v[2:3], 0, v[8:9]
	global_store_dwordx2 v[8:9], v[6:7], off
	ds_read_b128 v[6:9], v0 offset:50944
	s_waitcnt lgkmcnt(0)
	v_pk_add_f32 v[6:7], v[6:7], 0 op_sel_hi:[1,0]
	s_nop 0
	v_mul_f32_e32 v5, 0xbfb8aa3b, v6
	v_exp_f32_e32 v5, v5
	v_pk_add_f32 v[8:9], v[8:9], 0 op_sel_hi:[1,0]
	v_add_f32_e32 v5, 1.0, v5
	v_rcp_f32_e32 v10, v5
	v_mul_f32_e32 v5, 0xbfb8aa3b, v7
	v_exp_f32_e32 v5, v5
	s_nop 0
	v_add_f32_e32 v5, 1.0, v5
	v_rcp_f32_e32 v11, v5
	v_mul_f32_e32 v5, 0xbfb8aa3b, v8
	v_exp_f32_e32 v5, v5
	v_pk_mul_f32 v[6:7], v[6:7], v[10:11]
	s_nop 0
	v_cvt_pk_bf16_f32 v6, v6, v7
	v_add_f32_e32 v5, 1.0, v5
	v_rcp_f32_e32 v10, v5
	v_mul_f32_e32 v5, 0xbfb8aa3b, v9
	v_exp_f32_e32 v5, v5
	s_nop 0
	v_add_f32_e32 v5, 1.0, v5
	v_rcp_f32_e32 v11, v5
	s_nop 0
	v_pk_mul_f32 v[8:9], v[8:9], v[10:11]
	s_nop 0
	v_cvt_pk_bf16_f32 v7, v8, v9
	v_add_u32_e32 v8, 0x60, v4
	v_ashrrev_i32_e32 v9, 31, v8
	v_lshlrev_b64 v[8:9], 11, v[8:9]
	v_lshl_add_u64 v[8:9], v[2:3], 0, v[8:9]
	global_store_dwordx2 v[8:9], v[6:7], off
	ds_read_b128 v[6:9], v0 offset:59392
	v_add_u32_e32 v4, 0x70, v4
	v_ashrrev_i32_e32 v5, 31, v4
	v_lshlrev_b64 v[4:5], 11, v[4:5]
	v_lshl_add_u64 v[2:3], v[2:3], 0, v[4:5]
	s_waitcnt lgkmcnt(0)
	v_pk_add_f32 v[6:7], v[6:7], 0 op_sel_hi:[1,0]
	v_pk_add_f32 v[8:9], v[8:9], 0 op_sel_hi:[1,0]
	v_mul_f32_e32 v0, 0xbfb8aa3b, v6
	v_exp_f32_e32 v0, v0
	s_nop 0
	v_add_f32_e32 v0, 1.0, v0
	v_rcp_f32_e32 v10, v0
	v_mul_f32_e32 v0, 0xbfb8aa3b, v7
	v_exp_f32_e32 v0, v0
	s_nop 0
	v_add_f32_e32 v0, 1.0, v0
	v_rcp_f32_e32 v11, v0
	v_mul_f32_e32 v0, 0xbfb8aa3b, v8
	v_exp_f32_e32 v0, v0
	v_pk_mul_f32 v[6:7], v[6:7], v[10:11]
	s_nop 0
	v_cvt_pk_bf16_f32 v6, v6, v7
	v_add_f32_e32 v0, 1.0, v0
	v_rcp_f32_e32 v10, v0
	v_mul_f32_e32 v0, 0xbfb8aa3b, v9
	v_exp_f32_e32 v0, v0
	s_nop 0
	v_add_f32_e32 v0, 1.0, v0
	v_rcp_f32_e32 v11, v0
	s_nop 0
	v_pk_mul_f32 v[8:9], v[8:9], v[10:11]
	s_nop 0
	v_cvt_pk_bf16_f32 v7, v8, v9
	global_store_dwordx2 v[2:3], v[6:7], off

; #define G_STORE(ST, S, unused) do { char* d_ = smem + (ST) * STAGE; \
;     *(uint4*)(d_ + alo[0]) = S##a0; *(uint4*)(d_ + alo[1]) = S##a1; *(uint4*)(d_ + alo[2]) = S##a2; *(uint4*)(d_ + alo[3]) = S##a3; \
;     *(uint4*)(d_ + blo[0]) = S##b0; *(uint4*)(d_ + blo[1]) = S##b1; \
;     if (NBCH == 4) { *(uint4*)(d_ + blo[NBCH - 2]) = S##b2; *(uint4*)(d_ + blo[NBCH - 1]) = S##b3; } } while (0)
; template <int NJ, class RowA>
; DI void gemm_main(f32x16 (&acc)[2][NJ], const bf16_t* __restrict__ A, RowA rowA, size_t kstrideA, int m0, int Mmax,
;                   const bf16_t* __restrict__ Bt, size_t ldb, int n0, int nk, char* smem) {
;     ...
;   __syncthreads();
;   G_LOAD(x0, 0, 0);
;   G_LOAD(x1, 0, 1);
;   G_STORE(0, x0, 0);
;   __syncthreads();
; #pragma unroll 1
;   for (int kt = 0; kt < nk; kt += 2) {
;     G_LOAD(x0, 0, (kt + 2 < nk ? kt + 2 : nk - 1));
;     G_COMPUTE(0);
;     G_STORE(1, x1, 0);
;     __syncthreads();
;     G_LOAD(x1, 0, (kt + 3 < nk ? kt + 3 : nk - 1));
;     G_COMPUTE(1);
;     G_STORE(0, x0, 0);
;     __syncthreads();
;   }
.Lpeel_tail_2149:
	ds_read_b128 v[166:169], v0
	ds_read_b128 v[170:173], v139 offset:18432
	ds_read_b128 v[174:177], v139 offset:23040
	ds_read_b128 v[178:181], v0 offset:4608
	s_add_i32 s1, s0, 4
	s_min_u32 s1, s1, 15
	s_lshl_b32 s14, s1, 7
	v_lshl_add_u64 v[98:99], v[122:123], 0, s[14:15]
	v_lshl_add_u64 v[102:103], v[124:125], 0, s[14:15]
	v_lshl_add_u64 v[106:107], v[126:127], 0, s[14:15]
	v_lshl_add_u64 v[110:111], v[128:129], 0, s[14:15]
	v_lshl_add_u64 v[114:115], v[130:131], 0, s[14:15]
	v_lshl_add_u64 v[118:119], v[132:133], 0, s[14:15]
	s_add_i32 s0, s0, 2
	v_lshl_add_u64 v[158:159], v[134:135], 0, s[14:15]
	v_lshl_add_u64 v[160:161], v[136:137], 0, s[14:15]
	s_setprio 1
	ds_read_b128 v[182:185], v0 offset:32
	ds_read_b128 v[186:189], v139 offset:18464
	ds_read_b128 v[190:193], v139 offset:23072
	ds_read_b128 v[194:197], v0 offset:4640
	s_waitcnt lgkmcnt(4)
	v_mfma_f32_32x32x16_bf16 v[50:65], v[166:169], v[170:173], v[50:65]
	v_mfma_f32_32x32x16_bf16 v[34:49], v[166:169], v[174:177], v[34:49]
	v_mfma_f32_32x32x16_bf16 v[18:33], v[178:181], v[170:173], v[18:33]
	v_mfma_f32_32x32x16_bf16 v[2:17], v[178:181], v[174:177], v[2:17]
	ds_read_b128 v[166:169], v0 offset:64
	ds_read_b128 v[170:173], v139 offset:18496
	ds_read_b128 v[174:177], v139 offset:23104
	ds_read_b128 v[178:181], v0 offset:4672
	s_waitcnt lgkmcnt(4)
	v_mfma_f32_32x32x16_bf16 v[50:65], v[182:185], v[186:189], v[50:65]
	v_mfma_f32_32x32x16_bf16 v[34:49], v[182:185], v[190:193], v[34:49]
	v_mfma_f32_32x32x16_bf16 v[18:33], v[194:197], v[186:189], v[18:33]
	v_mfma_f32_32x32x16_bf16 v[2:17], v[194:197], v[190:193], v[2:17]
	ds_read_b128 v[182:185], v0 offset:96
	ds_read_b128 v[186:189], v139 offset:18528
	ds_read_b128 v[190:193], v139 offset:23136
	ds_read_b128 v[194:197], v0 offset:4704
	s_waitcnt lgkmcnt(4)
	v_mfma_f32_32x32x16_bf16 v[50:65], v[166:169], v[170:173], v[50:65]
	s_waitcnt vmcnt(0)
	ds_write_b128 v138, v[74:77] offset:36864
	v_mfma_f32_32x32x16_bf16 v[34:49], v[166:169], v[174:177], v[34:49]
	ds_write_b128 v140, v[78:81] offset:36864
	v_mfma_f32_32x32x16_bf16 v[18:33], v[178:181], v[170:173], v[18:33]
	ds_write_b128 v142, v[82:85] offset:36864
	v_mfma_f32_32x32x16_bf16 v[2:17], v[178:181], v[174:177], v[2:17]
	ds_write_b128 v144, v[86:89] offset:36864
	s_waitcnt lgkmcnt(4)
	v_mfma_f32_32x32x16_bf16 v[50:65], v[182:185], v[186:189], v[50:65]
	ds_write_b128 v138, v[90:93] offset:55296
	v_mfma_f32_32x32x16_bf16 v[34:49], v[182:185], v[190:193], v[34:49]
	ds_write_b128 v140, v[94:97] offset:55296
	v_mfma_f32_32x32x16_bf16 v[18:33], v[194:197], v[186:189], v[18:33]
	ds_write_b128 v142, v[66:69] offset:55296
	v_mfma_f32_32x32x16_bf16 v[2:17], v[194:197], v[190:193], v[2:17]
	ds_write_b128 v144, v[70:73] offset:55296
	s_setprio 0
	s_min_u32 s1, s0, 12
	s_lshl_b32 s14, s1, 7
	v_lshl_add_u64 v[66:67], v[122:123], 0, s[14:15]
	v_lshl_add_u64 v[68:69], v[124:125], 0, s[14:15]
	v_lshl_add_u64 v[70:71], v[126:127], 0, s[14:15]
	v_lshl_add_u64 v[72:73], v[128:129], 0, s[14:15]
	v_lshl_add_u64 v[90:91], v[130:131], 0, s[14:15]
	v_lshl_add_u64 v[94:95], v[132:133], 0, s[14:15]
	s_waitcnt lgkmcnt(0)
	s_barrier
	ds_read_b128 v[166:169], v0 offset:36864
	ds_read_b128 v[170:173], v139 offset:55296
	ds_read_b128 v[174:177], v139 offset:59904
	ds_read_b128 v[178:181], v0 offset:41472
	v_lshl_add_u64 v[154:155], v[134:135], 0, s[14:15]
	v_lshl_add_u64 v[156:157], v[136:137], 0, s[14:15]
	s_setprio 1
	ds_read_b128 v[182:185], v0 offset:36896
	ds_read_b128 v[186:189], v139 offset:55328
	ds_read_b128 v[190:193], v139 offset:59936
	ds_read_b128 v[194:197], v0 offset:41504
	s_waitcnt lgkmcnt(4)
	v_mfma_f32_32x32x16_bf16 v[50:65], v[166:169], v[170:173], v[50:65]
	v_mfma_f32_32x32x16_bf16 v[34:49], v[166:169], v[174:177], v[34:49]
	v_mfma_f32_32x32x16_bf16 v[18:33], v[178:181], v[170:173], v[18:33]
	v_mfma_f32_32x32x16_bf16 v[2:17], v[178:181], v[174:177], v[2:17]
	ds_read_b128 v[166:169], v0 offset:36928
	ds_read_b128 v[170:173], v139 offset:55360
	ds_read_b128 v[174:177], v139 offset:59968
	ds_read_b128 v[178:181], v0 offset:41536
	s_waitcnt lgkmcnt(4)
	v_mfma_f32_32x32x16_bf16 v[50:65], v[182:185], v[186:189], v[50:65]
	v_mfma_f32_32x32x16_bf16 v[34:49], v[182:185], v[190:193], v[34:49]
	v_mfma_f32_32x32x16_bf16 v[18:33], v[194:197], v[186:189], v[18:33]
	v_mfma_f32_32x32x16_bf16 v[2:17], v[194:197], v[190:193], v[2:17]
	ds_read_b128 v[182:185], v0 offset:36960
	ds_read_b128 v[186:189], v139 offset:55392
	ds_read_b128 v[190:193], v139 offset:60000
	ds_read_b128 v[194:197], v0 offset:41568
	s_waitcnt lgkmcnt(4)
	v_mfma_f32_32x32x16_bf16 v[50:65], v[166:169], v[170:173], v[50:65]
	v_mfma_f32_32x32x16_bf16 v[34:49], v[166:169], v[174:177], v[34:49]
	v_mfma_f32_32x32x16_bf16 v[18:33], v[178:181], v[170:173], v[18:33]
	v_mfma_f32_32x32x16_bf16 v[2:17], v[178:181], v[174:177], v[2:17]
	s_waitcnt lgkmcnt(0)
	v_mfma_f32_32x32x16_bf16 v[50:65], v[182:185], v[186:189], v[50:65]
	v_mfma_f32_32x32x16_bf16 v[34:49], v[182:185], v[190:193], v[34:49]
	v_mfma_f32_32x32x16_bf16 v[18:33], v[194:197], v[186:189], v[18:33]
	v_mfma_f32_32x32x16_bf16 v[2:17], v[194:197], v[190:193], v[2:17]
	s_setprio 0
	s_cmp_lt_u32 s0, 14
	s_waitcnt lgkmcnt(0)
	s_barrier
; #define TIDX (tid_launder())
; DI int crow(int reg, int hh) { return (reg & 3) + 8 * (reg >> 2) + 4 * hh; }
; template <int NJ>
; DI void acc_to_ct(const f32x16 (&acc)[2][NJ], float* Ct) {
;   const int lane = TIDX & 63, wid = TIDX >> 6, wm = wid >> 1, wn = wid & 1;
;   const int r = lane & 31, hh = lane >> 5;
; #pragma unroll
;   for (int i = 0; i < 2; ++i)
; #pragma unroll
;     for (int j = 0; j < NJ; ++j)
; #pragma unroll
;       for (int e = 0; e < 16; ++e) Ct[(wm * 64 + i * 32 + crow(e, hh)) * 132 + wn * 32 * NJ + j * 32 + r] = acc[i][j][e];
;   __syncthreads();
; DI void inproj_tile(const Params& p, int l, int mt, int tn, char* smem) {
;     ...
;   if (tn <= 3) {
;     epi_rownorm(Ct, rn, 64);
;     const float* g = tn < 2 ? p.a_q_norm + l * 64 : p.c_q_norm + l * 64;
;     epi_store64(Ct, 0, rn, 0, g, false, nullptr, p.projA, LDA_A, tn * 128, m0, T_TOK);
;     epi_store64(Ct, 64, rn, 1, g, false, nullptr, p.projA, LDA_A, tn * 128 + 64, m0, T_TOK);
;   } else if (tn == 4) {
;     epi_rownorm(Ct, rn, 128);
;     const float* g = p.a_kv_norm + l * 128;
;     epi_store64(Ct, 0, rn, 0, g, false, nullptr, p.projA, LDA_A, 512, m0, T_TOK);
;     epi_store64(Ct, 64, rn, 1, g + 64, false, nullptr, p.projA, LDA_A, 576, m0, T_TOK);
;   } else if (tn <= 8) {
;     epi_store64(Ct, 0, nullptr, 0, nullptr, false, nullptr, p.projA, LDA_A, tn * 128, m0, T_TOK);
;     epi_store64(Ct, 64, nullptr, 0, nullptr, false, nullptr, p.projA, LDA_A, tn * 128 + 64, m0, T_TOK);
;   } else if (tn == 9) {
;     epi_storeKF(Ct, 0, nullptr, 0, nullptr, p.kidxF + ((size_t)b * 64 + s0 / 32) * 2048);
;     epi_store64(Ct, 64, nullptr, 0, nullptr, false, nullptr, p.projA, LDA_A, tn * 128 + 64, m0, T_TOK);
;   } else if (tn == 10) {
;     epi_rownorm(Ct, rn, 64);
;     epi_store64(Ct, 0, nullptr, 0, nullptr, false, nullptr, p.projA, LDA_A, 1280, m0, T_TOK);
;     epi_storeKF(Ct, 64, rn, 1, p.c_k_norm + (l * 3 + 1) * 64, p.kselF + ((size_t)b * 64 + s0 / 32) * 2048);
;   } else if (tn == 11) {
;     epi_rownorm(Ct, rn, 64);
;     epi_storeKF(Ct, 0, rn, 0, p.c_k_norm + (l * 3 + 2) * 64, p.kwinF + ((size_t)b * 64 + s0 / 32) * 2048);
;     epi_storeVF(Ct, 64, p.vselT + ((size_t)b * 64 + s0 / 32) * 2048);
;   } else if (tn == 12) {
;     epi_storeVF(Ct, 0, p.vwinT + ((size_t)b * 64 + s0 / 32) * 2048);
	v_mov_b32_e32 v0, v230
	s_waitcnt vmcnt(1)
	v_mov_b32_e32 v66, v230
	v_and_b32_e32 v67, 31, v0
	v_lshrrev_b32_e32 v0, 3, v0
	v_and_b32_e32 v0, 4, v0
	v_lshrrev_b32_e32 v68, 1, v66
	v_and_or_b32 v0, v68, s47, v0
	v_and_or_b32 v66, v66, 64, v67
	v_mul_lo_u32 v0, v0, s79
	v_lshl_add_u32 v0, v66, 2, v0
	ds_write2_b32 v0, v50, v34 offset1:32
	ds_write2_b32 v0, v51, v35 offset0:132 offset1:164
	v_add_u32_e32 v34, 0x400, v0
	ds_write2_b32 v34, v52, v36 offset0:8 offset1:40
	ds_write2_b32 v34, v53, v37 offset0:140 offset1:172
	v_add_u32_e32 v34, 0x1000, v0
	ds_write2_b32 v34, v54, v38 offset0:32 offset1:64
	ds_write2_b32 v34, v55, v39 offset0:164 offset1:196
	v_add_u32_e32 v34, 0x1400, v0
	ds_write2_b32 v34, v56, v40 offset0:40 offset1:72
	ds_write2_b32 v34, v57, v41 offset0:172 offset1:204
	v_add_u32_e32 v34, 0x2000, v0
	ds_write2_b32 v34, v58, v42 offset0:64 offset1:96
	ds_write2_b32 v34, v59, v43 offset0:196 offset1:228
	v_add_u32_e32 v34, 0x2400, v0
	ds_write2_b32 v34, v60, v44 offset0:72 offset1:104
	ds_write2_b32 v34, v61, v45 offset0:204 offset1:236
	v_add_u32_e32 v34, 0x3000, v0
	ds_write2_b32 v34, v62, v46 offset0:96 offset1:128
	v_add_u32_e32 v34, 0x3200, v0
	ds_write2_b32 v34, v63, v47 offset0:100 offset1:132
	v_add_u32_e32 v34, 0x3400, v0
	ds_write2_b32 v34, v64, v48 offset0:104 offset1:136
	v_add_u32_e32 v34, 0x3600, v0
	ds_write2_b32 v34, v65, v49 offset0:108 offset1:140
	v_add_u32_e32 v34, 0x4000, v0
	ds_write2_b32 v34, v18, v2 offset0:128 offset1:160
	v_add_u32_e32 v2, 0x4400, v0
	ds_write2_b32 v2, v19, v3 offset0:4 offset1:36
	ds_write2_b32 v2, v20, v4 offset0:136 offset1:168
	v_add_u32_e32 v2, 0x4800, v0
	ds_write2_b32 v2, v21, v5 offset0:12 offset1:44
	v_add_u32_e32 v2, 0x5000, v0
	ds_write2_b32 v2, v22, v6 offset0:160 offset1:192
	v_add_u32_e32 v2, 0x5400, v0
	ds_write2_b32 v2, v23, v7 offset0:36 offset1:68
	ds_write2_b32 v2, v24, v8 offset0:168 offset1:200
	v_add_u32_e32 v2, 0x5800, v0
	ds_write2_b32 v2, v25, v9 offset0:44 offset1:76
	v_add_u32_e32 v2, 0x6000, v0
	ds_write2_b32 v2, v26, v10 offset0:192 offset1:224
	v_add_u32_e32 v2, 0x6400, v0
	ds_write2_b32 v2, v27, v11 offset0:68 offset1:100
	ds_write2_b32 v2, v28, v12 offset0:200 offset1:232
	v_add_u32_e32 v2, 0x6800, v0
	ds_write2_b32 v2, v29, v13 offset0:76 offset1:108
	v_add_u32_e32 v2, 0x7200, v0
	ds_write2_b32 v2, v30, v14 offset0:96 offset1:128
	v_add_u32_e32 v2, 0x7400, v0
	ds_write2_b32 v2, v31, v15 offset0:100 offset1:132
	v_add_u32_e32 v2, 0x7600, v0
	v_add_u32_e32 v0, 0x7800, v0
	s_cmp_gt_u32 s35, 3
	s_mov_b64 s[0:1], -1
	ds_write2_b32 v2, v32, v16 offset0:104 offset1:136
	ds_write2_b32 v0, v33, v17 offset0:108 offset1:140
	s_waitcnt lgkmcnt(0)
	s_barrier
	s_cbranch_scc0 .LBB0_2277
	s_cmp_lg_u32 s35, 4
	s_cbranch_scc0 .LBB0_2236
	s_cmp_gt_u32 s35, 8
	s_cbranch_scc0 .LBB0_2233
	s_ashr_i32 s0, s2, 6
	s_add_i32 s2, s0, s3
	s_ashr_i32 s0, s13, 31
	s_lshr_b32 s0, s0, 21
	s_add_i32 s0, s13, s0
	s_and_b32 s0, s0, 0xfffff800
	s_sub_i32 s14, s13, s0
	s_mov_b64 s[0:1], -1
	s_mov_b64 s[6:7], 0
	s_cmp_lt_i32 s68, -1
	s_mov_b64 s[4:5], 0
	s_cbranch_scc1 .LBB0_2199
	s_cmp_gt_i32 s68, -1
	s_cbranch_scc0 .LBB0_2169
	s_cmp_eq_u32 s68, 0
	s_mov_b64 s[4:5], -1
	s_cbranch_scc0 .LBB0_2168
	v_mov_b32_e32 v2, v230
	s_movk_i32 s0, 0x400
	s_nop 0
	v_cmp_gt_i32_e32 vcc, s0, v2
	s_and_saveexec_b64 s[0:1], vcc
	s_movk_i32 s36, 0x2ff
	s_cbranch_execz .LBB0_2159
	s_ashr_i32 s3, s2, 31
	s_ashr_i32 s4, s14, 5
	v_readlane_b32 s16, v250, 34
	s_ashr_i32 s5, s4, 31
	s_lshl_b64 s[8:9], s[2:3], 18
	v_readlane_b32 s22, v250, 40
	v_readlane_b32 s23, v250, 41
	s_add_u32 s3, s22, s8
	s_addc_u32 s8, s23, s9
	s_lshl_b64 s[4:5], s[4:5], 12
	s_add_u32 s4, s3, s4
	v_and_b32_e32 v0, 31, v2
	s_addc_u32 s5, s8, s5
	v_lshlrev_b32_e32 v3, 2, v0
	v_lshlrev_b32_e32 v4, 3, v2
	s_mov_b64 s[8:9], 0
	v_readlane_b32 s17, v250, 35
	v_readlane_b32 s18, v250, 36
	v_readlane_b32 s19, v250, 37
	v_readlane_b32 s20, v250, 38
	v_readlane_b32 s21, v250, 39
	v_readlane_b32 s24, v250, 42
	v_readlane_b32 s25, v250, 43
	v_readlane_b32 s26, v250, 44
	v_readlane_b32 s27, v250, 45
	v_readlane_b32 s28, v250, 46
	v_readlane_b32 s29, v250, 47
	v_readlane_b32 s30, v250, 48
	v_readlane_b32 s31, v250, 49
